# dense item: tile staging moved inside the PV window and next K fragments prefetched across windows
# speedup vs baseline: 1.0115x; 1.0049x over previous
; #define LAS __attribute__((address_space(3)))
; DI int otid() { int t = threadIdx.x; asm volatile("" : "+v"(t)); return t; }
; template <int DK>
; DI void dense_attn_item(LAS unsigned char* lds, const bf16_t* Qb, int ldq, const bf16_t* Kb, int ldk, const bf16_t* Kpe, const bf16_t* Vt, int nkeys, float sl2, bf16_t* Ob) {
;     const int tid = otid(), lane = tid & 63, wid = tid >> 6, r16 = lane & 15, q4 = lane >> 4;
;     constexpr int KS = DK / 32, KCH = DK / 8, KROW = DK * 2 + 16, KTILE = 64 * KROW, VROW = 144, VTILE = 128 * VROW, NKL = (64 * KCH) / 512;
;     bf16x8 qf[2][KS];
; #pragma unroll
;     for (int qg = 0; qg < 2; ++qg)
; #pragma unroll
;         for (int ks = 0; ks < KS; ++ks) qf[qg][ks] = *(const bf16x8*)(Qb + (size_t)(wid * 32 + qg * 16 + r16) * ldq + ks * 32 + q4 * 8);
;     f32x4 oacc[2][8];
; #pragma unroll
;     for (int qg = 0; qg < 2; ++qg)
; #pragma unroll
;         for (int d = 0; d < 8; ++d) oacc[qg][d] = (f32x4){0.f, 0.f, 0.f, 0.f};
;     float mrun[2] = {-1e30f, -1e30f}, lsum[2] = {0.f, 0.f};
;     u32x4 kst[NKL], vst[2];
;     const int ntiles = nkeys >> 6;
;     ...
;     DA_LOAD(0); DA_STORE(0);
;     __syncthreads();
; DI void dense192_item(unsigned char* ws, LAS unsigned char* lds, int b, int h, int q0, int nk) {
;     const size_t rowb = (size_t)b * RB, row0 = rowb + q0;
;     dense_attn_item<192>(lds, (const bf16_t*)(ws + WS_QM) + row0 * 960 + h * 192, 960, (const bf16_t*)(ws + WS_KM) + rowb * 640 + h * 128, 640, (const bf16_t*)(ws + WS_KPE) + rowb * 64,
;                          (const bf16_t*)(ws + WS_VTM) + ((size_t)b * 640 + h * 128) * RB, nk, 0.07216878364870322f * 1.4426950408889634f, (bf16_t*)(ws + WS_YMIX) + row0 * DM + 768 + h * 128);
.LBB0_1146:
	s_mul_hi_u32 s71, s28, 0x66666667
	s_lshr_b32 s71, s71, 4
	s_lshr_b32 s73, s28, 3
	s_mul_i32 s62, s71, 5
	s_sub_u32 s73, s73, s62
	s_and_b32 s62, s28, 7
	s_lshl_b32 s62, s62, 8
	s_mul_i32 s75, s71, 0x900
	s_add_u32 s74, s75, s62
	s_addk_i32 s74, 0x100
	s_mul_i32 s62, s74, 0x780
	s_mul_i32 s63, s73, 0x180
	s_add_u32 s62, s62, s63
	s_add_u32 s62, s62, 0x1a3a0000
	s_add_u32 s10, s50, s62
	s_addc_u32 s11, s51, 0
	s_mul_i32 s62, s75, 0x500
	s_lshl_b32 s63, s73, 8
	s_add_u32 s62, s62, s63
	s_add_u32 s62, s62, 0x1b480000
	s_add_u32 s4, s50, s62
	s_addc_u32 s5, s51, 0
	s_mul_i32 s62, s75, 0x480
	s_add_u32 s62, s62, s63
	s_sub_u32 s76, 0x167ff00, s62
	s_mul_i32 s62, s71, 0x280
	s_lshl_b32 s63, s73, 7
	s_add_u32 s62, s62, s63
	s_mul_i32 s62, s62, 0x1200
	s_add_u32 s62, s62, 0x1bfc0000
	s_add_u32 s8, s50, s62
	s_addc_u32 s9, s51, 0
	s_lshl_b32 s62, s74, 12
	s_lshl_b32 s63, s73, 8
	s_add_u32 s62, s62, s63
	s_add_u32 s62, s62, 0x1d9a0600
	s_add_u32 s20, s50, s62
	s_addc_u32 s21, s51, 0
	s_mov_b32 s22, 0x3dd53b94
	v_mov_b32_e32 v254, s22
	s_mov_b32 s29, 0x41000000
	v_and_b32_e32 v192, 31, v202
	v_bfe_u32 v193, v202, 5, 1
	v_lshrrev_b32_e32 v194, 6, v202
	v_lshl_add_u32 v195, v194, 5, v192
	v_mul_u32_u24_e32 v196, 0x780, v195
	v_lshl_add_u32 v250, v193, 4, v196
	global_load_dwordx4 v[0:3], v250, s[10:11] offset:0
	global_load_dwordx4 v[4:7], v250, s[10:11] offset:32
	global_load_dwordx4 v[8:11], v250, s[10:11] offset:64
	global_load_dwordx4 v[12:15], v250, s[10:11] offset:96
	global_load_dwordx4 v[16:19], v250, s[10:11] offset:128
	global_load_dwordx4 v[20:23], v250, s[10:11] offset:160
	global_load_dwordx4 v[24:27], v250, s[10:11] offset:192
	global_load_dwordx4 v[28:31], v250, s[10:11] offset:224
	global_load_dwordx4 v[32:35], v250, s[10:11] offset:256
	global_load_dwordx4 v[36:39], v250, s[10:11] offset:288
	global_load_dwordx4 v[40:43], v250, s[10:11] offset:320
	global_load_dwordx4 v[44:47], v250, s[10:11] offset:352
	s_mov_b32 s62, 0xaaaaaab
	v_mov_b32_e32 v197, v202
	v_mul_hi_u32 v198, v197, s62
	v_mul_u32_u24_e32 v195, 24, v198
	v_sub_u32_e32 v199, v197, v195
	v_mul_u32_u24_e32 v195, 0x190, v198
	v_lshl_add_u32 v230, v199, 4, v195
	v_cmp_gt_u32_e32 vcc, 16, v199
	v_mul_u32_u24_e32 v195, 0x500, v198
	v_lshlrev_b32_e32 v196, 7, v198
	v_add_u32_e32 v196, s76, v196
	s_nop 1
	v_cndmask_b32_e32 v195, v196, v195, vcc
	v_lshl_add_u32 v224, v199, 4, v195
	v_mov_b32_e32 v195, 0x2000
	v_mov_b32_e32 v196, 0x14000
	v_cndmask_b32_e32 v227, v195, v196, vcc
	v_add_u32_e32 v197, 0x200, v202
	v_mul_hi_u32 v198, v197, s62
	v_mul_u32_u24_e32 v195, 24, v198
	v_sub_u32_e32 v199, v197, v195
	v_mul_u32_u24_e32 v195, 0x190, v198
	v_lshl_add_u32 v231, v199, 4, v195
	v_cmp_gt_u32_e32 vcc, 16, v199
	v_mul_u32_u24_e32 v195, 0x500, v198
	v_lshlrev_b32_e32 v196, 7, v198
	v_add_u32_e32 v196, s76, v196
	s_nop 1
	v_cndmask_b32_e32 v195, v196, v195, vcc
	v_lshl_add_u32 v225, v199, 4, v195
	v_mov_b32_e32 v195, 0x2000
	v_mov_b32_e32 v196, 0x14000
	v_cndmask_b32_e32 v228, v195, v196, vcc
	v_add_u32_e32 v197, 0x400, v202
	v_mul_hi_u32 v198, v197, s62
	v_mul_u32_u24_e32 v195, 24, v198
	v_sub_u32_e32 v199, v197, v195
	v_mul_u32_u24_e32 v195, 0x190, v198
	v_lshl_add_u32 v232, v199, 4, v195
	v_cmp_gt_u32_e32 vcc, 16, v199
	v_mul_u32_u24_e32 v195, 0x500, v198
	v_lshlrev_b32_e32 v196, 7, v198
	v_add_u32_e32 v196, s76, v196
	s_nop 1
	v_cndmask_b32_e32 v195, v196, v195, vcc
	v_lshl_add_u32 v226, v199, 4, v195
	v_mov_b32_e32 v195, 0x2000
	v_mov_b32_e32 v196, 0x14000
	v_cndmask_b32_e32 v229, v195, v196, vcc
	v_mov_b32_e32 v197, v202
	v_lshrrev_b32_e32 v198, 3, v197
	v_and_b32_e32 v199, 7, v197
	v_mul_u32_u24_e32 v195, 0x1200, v198
	v_lshl_add_u32 v233, v199, 4, v195
	v_mul_u32_u24_e32 v195, 0x90, v198
	v_lshl_add_u32 v195, v199, 4, v195
	v_add_u32_e32 v235, 0x12c00, v195
	v_add_u32_e32 v197, 0x200, v202
	v_lshrrev_b32_e32 v198, 3, v197
	v_and_b32_e32 v199, 7, v197
	v_mul_u32_u24_e32 v195, 0x1200, v198
	v_lshl_add_u32 v234, v199, 4, v195
	v_mul_u32_u24_e32 v195, 0x90, v198
	v_lshl_add_u32 v195, v199, 4, v195
	v_add_u32_e32 v236, 0x12c00, v195
	v_mul_u32_u24_e32 v195, 0x190, v192
	v_lshl_add_u32 v237, v193, 4, v195
	v_mul_u32_u24_e32 v195, 0x90, v192
	v_lshl_add_u32 v195, v193, 3, v195
	v_add_u32_e32 v238, 0x12c00, v195
	global_load_dwordx4 v[204:207], v224, s[4:5]
	global_load_dwordx4 v[208:211], v225, s[4:5]
	global_load_dwordx4 v[212:215], v226, s[4:5]
	global_load_dwordx4 v[216:219], v233, s[8:9]
	global_load_dwordx4 v[220:223], v234, s[8:9]
	v_add_u32_e32 v224, v224, v227
	v_add_u32_e32 v225, v225, v228
	v_add_u32_e32 v226, v226, v229
	s_add_u32 s8, s8, 0x80
	s_addc_u32 s9, s9, 0
	v_mov_b32_e32 v48, 0
	v_mov_b32_e32 v49, 0
	v_mov_b32_e32 v50, 0
	v_mov_b32_e32 v51, 0
	v_mov_b32_e32 v52, 0
	v_mov_b32_e32 v53, 0
	v_mov_b32_e32 v54, 0
	v_mov_b32_e32 v55, 0
	v_mov_b32_e32 v56, 0
	v_mov_b32_e32 v57, 0
	v_mov_b32_e32 v58, 0
	v_mov_b32_e32 v59, 0
	v_mov_b32_e32 v60, 0
	v_mov_b32_e32 v61, 0
	v_mov_b32_e32 v62, 0
	v_mov_b32_e32 v63, 0
	v_mov_b32_e32 v64, 0
	v_mov_b32_e32 v65, 0
	v_mov_b32_e32 v66, 0
	v_mov_b32_e32 v67, 0
	v_mov_b32_e32 v68, 0
	v_mov_b32_e32 v69, 0
	v_mov_b32_e32 v70, 0
	v_mov_b32_e32 v71, 0
	v_mov_b32_e32 v72, 0
	v_mov_b32_e32 v73, 0
	v_mov_b32_e32 v74, 0
	v_mov_b32_e32 v75, 0
	v_mov_b32_e32 v76, 0
	v_mov_b32_e32 v77, 0
	v_mov_b32_e32 v78, 0
	v_mov_b32_e32 v79, 0
	v_mov_b32_e32 v80, 0
	v_mov_b32_e32 v81, 0
	v_mov_b32_e32 v82, 0
	v_mov_b32_e32 v83, 0
	v_mov_b32_e32 v84, 0
	v_mov_b32_e32 v85, 0
	v_mov_b32_e32 v86, 0
	v_mov_b32_e32 v87, 0
	v_mov_b32_e32 v88, 0
	v_mov_b32_e32 v89, 0
	v_mov_b32_e32 v90, 0
	v_mov_b32_e32 v91, 0
	v_mov_b32_e32 v92, 0
	v_mov_b32_e32 v93, 0
	v_mov_b32_e32 v94, 0
	v_mov_b32_e32 v95, 0
	v_mov_b32_e32 v96, 0
	v_mov_b32_e32 v97, 0
	v_mov_b32_e32 v98, 0
	v_mov_b32_e32 v99, 0
	v_mov_b32_e32 v100, 0
	v_mov_b32_e32 v101, 0
	v_mov_b32_e32 v102, 0
	v_mov_b32_e32 v103, 0
	v_mov_b32_e32 v104, 0
	v_mov_b32_e32 v105, 0
	v_mov_b32_e32 v106, 0
	v_mov_b32_e32 v107, 0
	v_mov_b32_e32 v108, 0
	v_mov_b32_e32 v109, 0
	v_mov_b32_e32 v110, 0
	v_mov_b32_e32 v111, 0
	v_mov_b32_e32 v242, 0xf149f2ca
	v_mov_b32_e32 v244, 0
	s_waitcnt vmcnt(0)
	v_lshl_add_u32 v195, v194, 5, v192
	v_lshlrev_b32_e32 v195, 12, v195
	v_lshl_add_u32 v250, v193, 3, v195
	ds_write_b128 v230, v[204:207]
	ds_write_b128 v231, v[208:211]
	ds_write_b128 v232, v[212:215]
	ds_write_b128 v235, v[216:219]
	ds_write_b128 v236, v[220:223]
	s_waitcnt lgkmcnt(0)
	global_load_dwordx4 v[204:207], v224, s[4:5]
	global_load_dwordx4 v[208:211], v225, s[4:5]
	global_load_dwordx4 v[212:215], v226, s[4:5]
	global_load_dwordx4 v[216:219], v233, s[8:9]
	global_load_dwordx4 v[220:223], v234, s[8:9]
	s_barrier
; template <int DK>
; DI void dense_attn_item(LAS unsigned char* lds, const bf16_t* Qb, int ldq, const bf16_t* Kb, int ldk, const bf16_t* Kpe, const bf16_t* Vt, int nkeys, float sl2, bf16_t* Ob) {
;     ...
;     for (int kt = 0; kt < ntiles; ++kt) {
;         const int cur = kt & 1;
;         if (kt + 1 < ntiles) DA_LOAD((kt + 1) * 64);
;         const LAS unsigned char* kb_ = lds + cur * KTILE; const LAS unsigned char* vb_ = lds + 2 * KTILE + cur * VTILE;
; #pragma unroll
;         for (int kc = 0; kc < 2; ++kc) {
;             f32x4 sacc[2][2];
; #pragma unroll
;             for (int kb = 0; kb < 2; ++kb) {
;                 sacc[0][kb] = (f32x4){0.f, 0.f, 0.f, 0.f}; sacc[1][kb] = (f32x4){0.f, 0.f, 0.f, 0.f};
; #pragma unroll
;                 for (int kh = 0; kh < KS / 2; ++kh) {
;                     const bf16x8 k0 = *(const LAS bf16x8*)(kb_ + ((2 * kc + kb) * 16 + r16) * KROW + (2 * kh) * 64 + q4 * 16);
;                     const bf16x8 k1 = *(const LAS bf16x8*)(kb_ + ((2 * kc + kb) * 16 + r16) * KROW + (2 * kh + 1) * 64 + q4 * 16);
;                     __builtin_amdgcn_s_setprio(1);
;                     sacc[0][kb] = MFMA16(k0, qf[0][2 * kh], sacc[0][kb]); sacc[1][kb] = MFMA16(k0, qf[1][2 * kh], sacc[1][kb]);
;                     sacc[0][kb] = MFMA16(k1, qf[0][2 * kh + 1], sacc[0][kb]); sacc[1][kb] = MFMA16(k1, qf[1][2 * kh + 1], sacc[1][kb]);
;                     __builtin_amdgcn_s_setprio(0);
;                 }
;             }
;             bf16x8 pb[2];
; #pragma unroll
;             for (int qg = 0; qg < 2; ++qg) {
;                 float mx = fmaxf(fmaxf(fmaxf(sacc[qg][0][0], sacc[qg][0][1]), fmaxf(sacc[qg][0][2], sacc[qg][0][3])), fmaxf(fmaxf(sacc[qg][1][0], sacc[qg][1][1]), fmaxf(sacc[qg][1][2], sacc[qg][1][3])));
;                 mx = fmaxf(mx, __shfl_xor(mx, 16)); mx = fmaxf(mx, __shfl_xor(mx, 32));
;                 const float mnew = fmaxf(mrun[qg], mx * sl2), alpha = fast_exp2(mrun[qg] - mnew);
;                 mrun[qg] = mnew;
;                 float ps = 0.f;
; #pragma unroll
;                 for (int kb = 0; kb < 2; ++kb)
; #pragma unroll
;                     for (int j = 0; j < 4; ++j) { const float pv = fast_exp2(sacc[qg][kb][j] * sl2 - mnew); sacc[qg][kb][j] = pv; ps += pv; }
;                 lsum[qg] = lsum[qg] * alpha + ps;
; #pragma unroll
;                 for (int d = 0; d < 8; ++d) oacc[qg][d] *= alpha;
	v_mov_b32_e32 v239, v237
	ds_read_b128 v[144:147], v239 offset:0
	ds_read_b128 v[148:151], v239 offset:32
	ds_read_b128 v[152:155], v239 offset:64
	ds_read_b128 v[156:159], v239 offset:96
	ds_read_b128 v[160:163], v239 offset:128
	ds_read_b128 v[164:167], v239 offset:160
	s_waitcnt lgkmcnt(5)
	v_mfma_f32_32x32x16_bf16 v[112:127], v[144:147], v[0:3], 0
	ds_read_b128 v[144:147], v239 offset:192
	s_waitcnt lgkmcnt(5)
	v_mfma_f32_32x32x16_bf16 v[112:127], v[148:151], v[4:7], v[112:127]
	ds_read_b128 v[148:151], v239 offset:224
	s_waitcnt lgkmcnt(5)
	v_mfma_f32_32x32x16_bf16 v[112:127], v[152:155], v[8:11], v[112:127]
	ds_read_b128 v[152:155], v239 offset:256
	s_waitcnt lgkmcnt(5)
	v_mfma_f32_32x32x16_bf16 v[112:127], v[156:159], v[12:15], v[112:127]
	ds_read_b128 v[156:159], v239 offset:288
	s_waitcnt lgkmcnt(5)
	v_mfma_f32_32x32x16_bf16 v[112:127], v[160:163], v[16:19], v[112:127]
	ds_read_b128 v[160:163], v239 offset:320
	s_waitcnt lgkmcnt(5)
	v_mfma_f32_32x32x16_bf16 v[112:127], v[164:167], v[20:23], v[112:127]
	ds_read_b128 v[164:167], v239 offset:352
	s_waitcnt lgkmcnt(5)
	v_mfma_f32_32x32x16_bf16 v[112:127], v[144:147], v[24:27], v[112:127]
	s_waitcnt lgkmcnt(4)
	v_mfma_f32_32x32x16_bf16 v[112:127], v[148:151], v[28:31], v[112:127]
	s_waitcnt lgkmcnt(3)
	v_mfma_f32_32x32x16_bf16 v[112:127], v[152:155], v[32:35], v[112:127]
	s_waitcnt lgkmcnt(2)
	v_mfma_f32_32x32x16_bf16 v[112:127], v[156:159], v[36:39], v[112:127]
	s_waitcnt lgkmcnt(1)
	v_mfma_f32_32x32x16_bf16 v[112:127], v[160:163], v[40:43], v[112:127]
	s_waitcnt lgkmcnt(0)
	v_mfma_f32_32x32x16_bf16 v[112:127], v[164:167], v[44:47], v[112:127]
	ds_read_b128 v[144:147], v239 offset:12800
	ds_read_b128 v[148:151], v239 offset:12832
	ds_read_b128 v[152:155], v239 offset:12864
	ds_read_b128 v[156:159], v239 offset:12896
	ds_read_b128 v[160:163], v239 offset:12928
	ds_read_b128 v[164:167], v239 offset:12960
	s_mov_b32 s23, 0
	s_mov_b32 s27, 0
dn0_top:
	s_add_u32 s57, s27, 1
	s_cmp_eq_u32 s57, 3
	s_cselect_b32 s57, 0, s57
	s_mul_i32 s36, s27, 0x6400
	s_mul_i32 s54, s27, 0x4800
	s_mul_i32 s37, s57, 0x6400
	s_mul_i32 s56, s57, 0x4800
	v_add_u32_e32 v239, s36, v237
	v_add_u32_e32 v240, s37, v237
	v_add_u32_e32 v241, s54, v238
	v_add_u32_e32 v224, v224, v227
	v_add_u32_e32 v225, v225, v228
	v_add_u32_e32 v226, v226, v229
	s_add_u32 s8, s8, 0x80
	s_addc_u32 s9, s9, 0
	v_max3_f32 v193, v112, v113, v114
	v_max3_f32 v192, v115, v116, v117
	v_max3_f32 v193, v193, v118, v119
	v_max3_f32 v192, v192, v120, v121
	s_waitcnt lgkmcnt(5)
	v_mfma_f32_32x32x16_bf16 v[128:143], v[144:147], v[0:3], 0
	v_max3_f32 v193, v193, v122, v123
	v_max3_f32 v192, v192, v124, v125
	v_max3_f32 v193, v193, v126, v127
	v_max_f32_e32 v193, v193, v192
	v_mov_b32_e32 v192, v193
	ds_read_b128 v[144:147], v239 offset:12992
	s_waitcnt lgkmcnt(5)
	v_mfma_f32_32x32x16_bf16 v[128:143], v[148:151], v[4:7], v[128:143]
	s_nop 1
	v_permlane32_swap_b32_e32 v193, v192
	v_max_f32_e32 v193, v193, v192
	v_mul_f32_e32 v193, s22, v193
	v_max_f32_e32 v192, v242, v193
	ds_read_b128 v[148:151], v239 offset:13024
	s_waitcnt lgkmcnt(5)
	v_mfma_f32_32x32x16_bf16 v[128:143], v[152:155], v[8:11], v[128:143]
	v_sub_f32_e32 v193, v192, v242
	v_cmp_gt_f32_e64 s[68:69], v193, s29
	s_cmp_lg_u64 s[68:69], 0
	s_cselect_b64 s[68:69], -1, 0
	v_cndmask_b32_e64 v192, v242, v192, s[68:69]
	ds_read_b128 v[152:155], v239 offset:13056
	s_waitcnt lgkmcnt(5)
	v_mfma_f32_32x32x16_bf16 v[128:143], v[156:159], v[12:15], v[128:143]
	v_sub_f32_e32 v193, v242, v192
	v_exp_f32_e32 v246, v193
	v_mov_b32_e32 v242, v192
	v_pk_fma_f32 v[112:113], v[112:113], v[254:255], v[192:193] op_sel_hi:[1,0,0] neg_lo:[0,0,1] neg_hi:[0,0,1]
	v_pk_fma_f32 v[114:115], v[114:115], v[254:255], v[192:193] op_sel_hi:[1,0,0] neg_lo:[0,0,1] neg_hi:[0,0,1]
	ds_read_b128 v[156:159], v239 offset:13088
	s_waitcnt lgkmcnt(5)
	v_mfma_f32_32x32x16_bf16 v[128:143], v[160:163], v[16:19], v[128:143]
	v_pk_fma_f32 v[116:117], v[116:117], v[254:255], v[192:193] op_sel_hi:[1,0,0] neg_lo:[0,0,1] neg_hi:[0,0,1]
	v_pk_fma_f32 v[118:119], v[118:119], v[254:255], v[192:193] op_sel_hi:[1,0,0] neg_lo:[0,0,1] neg_hi:[0,0,1]
	v_pk_fma_f32 v[120:121], v[120:121], v[254:255], v[192:193] op_sel_hi:[1,0,0] neg_lo:[0,0,1] neg_hi:[0,0,1]
	v_pk_fma_f32 v[122:123], v[122:123], v[254:255], v[192:193] op_sel_hi:[1,0,0] neg_lo:[0,0,1] neg_hi:[0,0,1]
	v_pk_fma_f32 v[124:125], v[124:125], v[254:255], v[192:193] op_sel_hi:[1,0,0] neg_lo:[0,0,1] neg_hi:[0,0,1]
	ds_read_b128 v[160:163], v239 offset:13120
	s_waitcnt lgkmcnt(5)
	v_mfma_f32_32x32x16_bf16 v[128:143], v[164:167], v[20:23], v[128:143]
	v_pk_fma_f32 v[126:127], v[126:127], v[254:255], v[192:193] op_sel_hi:[1,0,0] neg_lo:[0,0,1] neg_hi:[0,0,1]
	v_exp_f32_e32 v112, v112
	v_exp_f32_e32 v113, v113
	v_exp_f32_e32 v114, v114
	v_exp_f32_e32 v115, v115
	ds_read_b128 v[164:167], v239 offset:13152
	s_waitcnt lgkmcnt(5)
	v_mfma_f32_32x32x16_bf16 v[128:143], v[144:147], v[24:27], v[128:143]
	v_exp_f32_e32 v116, v116
	v_exp_f32_e32 v117, v117
	v_exp_f32_e32 v118, v118
	v_exp_f32_e32 v119, v119
	v_exp_f32_e32 v120, v120
	ds_read_b64 v[168:169], v241 offset:0
	ds_read_b64 v[170:171], v241 offset:16
	s_waitcnt lgkmcnt(6)
	v_mfma_f32_32x32x16_bf16 v[128:143], v[148:151], v[28:31], v[128:143]
	v_exp_f32_e32 v121, v121
	v_exp_f32_e32 v122, v122
	v_exp_f32_e32 v123, v123
	v_exp_f32_e32 v124, v124
	v_exp_f32_e32 v125, v125
	ds_read_b64 v[172:173], v241 offset:32
	ds_read_b64 v[174:175], v241 offset:48
	s_waitcnt lgkmcnt(7)
	v_mfma_f32_32x32x16_bf16 v[128:143], v[152:155], v[32:35], v[128:143]
	v_exp_f32_e32 v126, v126
	v_exp_f32_e32 v127, v127
	v_pk_add_f32 v[196:197], v[112:113], v[114:115]
	v_pk_add_f32 v[198:199], v[116:117], v[118:119]
	v_pk_add_f32 v[196:197], v[196:197], v[120:121]
	ds_read_b64 v[176:177], v241 offset:4608
	ds_read_b64 v[178:179], v241 offset:4624
	s_waitcnt lgkmcnt(8)
	v_mfma_f32_32x32x16_bf16 v[128:143], v[156:159], v[36:39], v[128:143]
	v_pk_add_f32 v[198:199], v[198:199], v[122:123]
	v_pk_add_f32 v[196:197], v[196:197], v[124:125]
	v_pk_add_f32 v[198:199], v[198:199], v[126:127]
	v_pk_add_f32 v[196:197], v[196:197], v[198:199]
	v_add_f32_e32 v193, v196, v197
	ds_read_b64 v[180:181], v241 offset:4640
	ds_read_b64 v[182:183], v241 offset:4656
	s_waitcnt lgkmcnt(9)
	v_mfma_f32_32x32x16_bf16 v[128:143], v[160:163], v[40:43], v[128:143]
	v_fma_f32 v244, v244, v246, v193
	v_cvt_pk_bf16_f32 v184, v112, v113
	v_cvt_pk_bf16_f32 v185, v114, v115
	v_cvt_pk_bf16_f32 v186, v116, v117
	v_cvt_pk_bf16_f32 v187, v118, v119
	s_waitcnt lgkmcnt(8)
	v_mfma_f32_32x32x16_bf16 v[128:143], v[164:167], v[44:47], v[128:143]
	v_cvt_pk_bf16_f32 v188, v120, v121
	v_cvt_pk_bf16_f32 v189, v122, v123
	v_cvt_pk_bf16_f32 v190, v124, v125
	v_cvt_pk_bf16_f32 v191, v126, v127
	s_mov_b64 vcc, s[68:69]
	s_cbranch_vccz dn0_nr1
; #define LAS __attribute__((address_space(3)))
; DI unsigned cvt_pk_bf16(float lo, float hi) { unsigned r; asm volatile("v_cvt_pk_bf16_f32 %0, %1, %2" : "=v"(r) : "v"(lo), "v"(hi)); return r; }
; #define MFMA16(a, b, c) __builtin_amdgcn_mfma_f32_16x16x32_bf16((a), (b), (c), 0, 0, 0)
; template <int DK>
; DI void dense_attn_item(LAS unsigned char* lds, const bf16_t* Qb, int ldq, const bf16_t* Kb, int ldk, const bf16_t* Kpe, const bf16_t* Vt, int nkeys, float sl2, bf16_t* Ob) {
;     ...
;                 for (int d = 0; d < 8; ++d) oacc[qg][d] *= alpha;
;                 u32x4 w; w.x = cvt_pk_bf16(sacc[qg][0][0], sacc[qg][0][1]); w.y = cvt_pk_bf16(sacc[qg][0][2], sacc[qg][0][3]);
;                 w.z = cvt_pk_bf16(sacc[qg][1][0], sacc[qg][1][1]); w.w = cvt_pk_bf16(sacc[qg][1][2], sacc[qg][1][3]);
;                 pb[qg] = __builtin_bit_cast(bf16x8, w);
;             }
; #pragma unroll
;             for (int dh = 0; dh < 4; ++dh) {
;                 bf16x8 vfr[2];
; #pragma unroll
;                 for (int d4 = 0; d4 < 2; ++d4) {
;                     const int d = dh * 2 + d4;
;                     const u32x2 lo = *(const LAS u32x2*)(vb_ + (d * 16 + r16) * VROW + (kc * 32 + q4 * 4) * 2);
;                     const u32x2 hi = *(const LAS u32x2*)(vb_ + (d * 16 + r16) * VROW + (kc * 32 + 16 + q4 * 4) * 2);
;                     u32x4 w; w.x = lo.x; w.y = lo.y; w.z = hi.x; w.w = hi.y;
;                     vfr[d4] = __builtin_bit_cast(bf16x8, w);
;                 }
;                 __builtin_amdgcn_s_setprio(1);
; #pragma unroll
;                 for (int d4 = 0; d4 < 2; ++d4) { const int d = dh * 2 + d4; oacc[0][d] = MFMA16(vfr[d4], pb[0], oacc[0][d]); oacc[1][d] = MFMA16(vfr[d4], pb[1], oacc[1][d]); }
;                 __builtin_amdgcn_s_setprio(0);
;             }
;         }
;         if (kt + 1 < ntiles) DA_STORE(cur ^ 1);
	v_add_u32_e32 v196, s37, v230
	v_add_u32_e32 v197, s37, v231
	v_add_u32_e32 v198, s37, v232
	v_add_u32_e32 v199, s56, v235
	v_add_u32_e32 v200, s56, v236
	s_waitcnt vmcnt(0)
	ds_write_b128 v196, v[204:207]
	ds_write_b128 v197, v[208:211]
	ds_write_b128 v198, v[212:215]
	ds_write_b128 v199, v[216:219]
	ds_write_b128 v200, v[220:223]
	v_pk_mul_f32 v[48:49], v[48:49], v[246:247] op_sel_hi:[1,0]
	v_pk_mul_f32 v[50:51], v[50:51], v[246:247] op_sel_hi:[1,0]
	v_pk_mul_f32 v[52:53], v[52:53], v[246:247] op_sel_hi:[1,0]
	v_pk_mul_f32 v[54:55], v[54:55], v[246:247] op_sel_hi:[1,0]
	v_pk_mul_f32 v[56:57], v[56:57], v[246:247] op_sel_hi:[1,0]
	v_pk_mul_f32 v[58:59], v[58:59], v[246:247] op_sel_hi:[1,0]
	v_pk_mul_f32 v[60:61], v[60:61], v[246:247] op_sel_hi:[1,0]
	v_pk_mul_f32 v[62:63], v[62:63], v[246:247] op_sel_hi:[1,0]
	s_waitcnt lgkmcnt(11)
	v_mfma_f32_32x32x16_bf16 v[48:63], v[168:171], v[184:187], v[48:63]
	v_pk_mul_f32 v[64:65], v[64:65], v[246:247] op_sel_hi:[1,0]
	v_pk_mul_f32 v[66:67], v[66:67], v[246:247] op_sel_hi:[1,0]
	v_pk_mul_f32 v[68:69], v[68:69], v[246:247] op_sel_hi:[1,0]
	v_pk_mul_f32 v[70:71], v[70:71], v[246:247] op_sel_hi:[1,0]
	ds_read_b64 v[168:169], v241 offset:9216
	ds_read_b64 v[170:171], v241 offset:9232
	s_waitcnt lgkmcnt(11)
	v_mfma_f32_32x32x16_bf16 v[48:63], v[172:175], v[188:191], v[48:63]
	v_pk_mul_f32 v[72:73], v[72:73], v[246:247] op_sel_hi:[1,0]
	v_pk_mul_f32 v[74:75], v[74:75], v[246:247] op_sel_hi:[1,0]
	v_pk_mul_f32 v[76:77], v[76:77], v[246:247] op_sel_hi:[1,0]
	v_pk_mul_f32 v[78:79], v[78:79], v[246:247] op_sel_hi:[1,0]
	ds_read_b64 v[172:173], v241 offset:9248
	ds_read_b64 v[174:175], v241 offset:9264
	s_waitcnt lgkmcnt(11)
	v_mfma_f32_32x32x16_bf16 v[64:79], v[176:179], v[184:187], v[64:79]
	v_pk_mul_f32 v[80:81], v[80:81], v[246:247] op_sel_hi:[1,0]
	v_pk_mul_f32 v[82:83], v[82:83], v[246:247] op_sel_hi:[1,0]
	v_pk_mul_f32 v[84:85], v[84:85], v[246:247] op_sel_hi:[1,0]
	v_pk_mul_f32 v[86:87], v[86:87], v[246:247] op_sel_hi:[1,0]
	ds_read_b64 v[176:177], v241 offset:13824
	ds_read_b64 v[178:179], v241 offset:13840
	s_waitcnt lgkmcnt(11)
	v_mfma_f32_32x32x16_bf16 v[64:79], v[180:183], v[188:191], v[64:79]
	v_pk_mul_f32 v[88:89], v[88:89], v[246:247] op_sel_hi:[1,0]
	v_pk_mul_f32 v[90:91], v[90:91], v[246:247] op_sel_hi:[1,0]
	v_pk_mul_f32 v[92:93], v[92:93], v[246:247] op_sel_hi:[1,0]
	v_pk_mul_f32 v[94:95], v[94:95], v[246:247] op_sel_hi:[1,0]
	ds_read_b64 v[180:181], v241 offset:13856
	ds_read_b64 v[182:183], v241 offset:13872
	s_waitcnt lgkmcnt(6)
	global_load_dwordx4 v[204:207], v224, s[4:5]
	global_load_dwordx4 v[208:211], v225, s[4:5]
	global_load_dwordx4 v[212:215], v226, s[4:5]
	global_load_dwordx4 v[216:219], v233, s[8:9]
	global_load_dwordx4 v[220:223], v234, s[8:9]
	v_mfma_f32_32x32x16_bf16 v[80:95], v[168:171], v[184:187], v[80:95]
	v_pk_mul_f32 v[96:97], v[96:97], v[246:247] op_sel_hi:[1,0]
	v_pk_mul_f32 v[98:99], v[98:99], v[246:247] op_sel_hi:[1,0]
	v_pk_mul_f32 v[100:101], v[100:101], v[246:247] op_sel_hi:[1,0]
	v_pk_mul_f32 v[102:103], v[102:103], v[246:247] op_sel_hi:[1,0]
	s_nop 1
	s_waitcnt lgkmcnt(4)
	v_mfma_f32_32x32x16_bf16 v[80:95], v[172:175], v[188:191], v[80:95]
	v_pk_mul_f32 v[104:105], v[104:105], v[246:247] op_sel_hi:[1,0]
	v_pk_mul_f32 v[106:107], v[106:107], v[246:247] op_sel_hi:[1,0]
	v_pk_mul_f32 v[108:109], v[108:109], v[246:247] op_sel_hi:[1,0]
	v_pk_mul_f32 v[110:111], v[110:111], v[246:247] op_sel_hi:[1,0]
	s_nop 1
	s_waitcnt lgkmcnt(2)
	v_mfma_f32_32x32x16_bf16 v[96:111], v[176:179], v[184:187], v[96:111]
	s_waitcnt lgkmcnt(0)
	v_mfma_f32_32x32x16_bf16 v[96:111], v[180:183], v[188:191], v[96:111]
	s_branch dn0_jn1
dn0_nr1:
	s_nop 1
	v_add_u32_e32 v196, s37, v230
	v_add_u32_e32 v197, s37, v231
	v_add_u32_e32 v198, s37, v232
	v_add_u32_e32 v199, s56, v235
	v_add_u32_e32 v200, s56, v236
	s_waitcnt vmcnt(0)
	ds_write_b128 v196, v[204:207]
	ds_write_b128 v197, v[208:211]
	ds_write_b128 v198, v[212:215]
	ds_write_b128 v199, v[216:219]
	ds_write_b128 v200, v[220:223]
	s_waitcnt lgkmcnt(11)
	v_mfma_f32_32x32x16_bf16 v[48:63], v[168:171], v[184:187], v[48:63]
	ds_read_b64 v[168:169], v241 offset:9216
	ds_read_b64 v[170:171], v241 offset:9232
	s_waitcnt lgkmcnt(11)
	v_mfma_f32_32x32x16_bf16 v[48:63], v[172:175], v[188:191], v[48:63]
	ds_read_b64 v[172:173], v241 offset:9248
	ds_read_b64 v[174:175], v241 offset:9264
	s_waitcnt lgkmcnt(11)
	v_mfma_f32_32x32x16_bf16 v[64:79], v[176:179], v[184:187], v[64:79]
	ds_read_b64 v[176:177], v241 offset:13824
	ds_read_b64 v[178:179], v241 offset:13840
	s_waitcnt lgkmcnt(11)
	v_mfma_f32_32x32x16_bf16 v[64:79], v[180:183], v[188:191], v[64:79]
	ds_read_b64 v[180:181], v241 offset:13856
	ds_read_b64 v[182:183], v241 offset:13872
	s_waitcnt lgkmcnt(6)
	global_load_dwordx4 v[204:207], v224, s[4:5]
	global_load_dwordx4 v[208:211], v225, s[4:5]
	global_load_dwordx4 v[212:215], v226, s[4:5]
	global_load_dwordx4 v[216:219], v233, s[8:9]
	global_load_dwordx4 v[220:223], v234, s[8:9]
	v_mfma_f32_32x32x16_bf16 v[80:95], v[168:171], v[184:187], v[80:95]
	s_waitcnt lgkmcnt(4)
	v_mfma_f32_32x32x16_bf16 v[80:95], v[172:175], v[188:191], v[80:95]
	s_waitcnt lgkmcnt(2)
	v_mfma_f32_32x32x16_bf16 v[96:111], v[176:179], v[184:187], v[96:111]
	s_waitcnt lgkmcnt(0)
	v_mfma_f32_32x32x16_bf16 v[96:111], v[180:183], v[188:191], v[96:111]
; template <int DK>
; DI void dense_attn_item(LAS unsigned char* lds, const bf16_t* Qb, int ldq, const bf16_t* Kb, int ldk, const bf16_t* Kpe, const bf16_t* Vt, int nkeys, float sl2, bf16_t* Ob) {
;     ...
;         for (int kc = 0; kc < 2; ++kc) {
;             f32x4 sacc[2][2];
; #pragma unroll
;             for (int kb = 0; kb < 2; ++kb) {
;                 sacc[0][kb] = (f32x4){0.f, 0.f, 0.f, 0.f}; sacc[1][kb] = (f32x4){0.f, 0.f, 0.f, 0.f};
; #pragma unroll
;                 for (int kh = 0; kh < KS / 2; ++kh) {
;                     const bf16x8 k0 = *(const LAS bf16x8*)(kb_ + ((2 * kc + kb) * 16 + r16) * KROW + (2 * kh) * 64 + q4 * 16);
;                     const bf16x8 k1 = *(const LAS bf16x8*)(kb_ + ((2 * kc + kb) * 16 + r16) * KROW + (2 * kh + 1) * 64 + q4 * 16);
;                     __builtin_amdgcn_s_setprio(1);
;                     sacc[0][kb] = MFMA16(k0, qf[0][2 * kh], sacc[0][kb]); sacc[1][kb] = MFMA16(k0, qf[1][2 * kh], sacc[1][kb]);
;                     sacc[0][kb] = MFMA16(k1, qf[0][2 * kh + 1], sacc[0][kb]); sacc[1][kb] = MFMA16(k1, qf[1][2 * kh + 1], sacc[1][kb]);
;                     __builtin_amdgcn_s_setprio(0);
;                 }
;             }
;             bf16x8 pb[2];
; #pragma unroll
;             for (int qg = 0; qg < 2; ++qg) {
;                 float mx = fmaxf(fmaxf(fmaxf(sacc[qg][0][0], sacc[qg][0][1]), fmaxf(sacc[qg][0][2], sacc[qg][0][3])), fmaxf(fmaxf(sacc[qg][1][0], sacc[qg][1][1]), fmaxf(sacc[qg][1][2], sacc[qg][1][3])));
;                 mx = fmaxf(mx, __shfl_xor(mx, 16)); mx = fmaxf(mx, __shfl_xor(mx, 32));
;                 const float mnew = fmaxf(mrun[qg], mx * sl2), alpha = fast_exp2(mrun[qg] - mnew);
;                 mrun[qg] = mnew;
;                 float ps = 0.f;
; #pragma unroll
;                 for (int kb = 0; kb < 2; ++kb)
; #pragma unroll
;                     for (int j = 0; j < 4; ++j) { const float pv = fast_exp2(sacc[qg][kb][j] * sl2 - mnew); sacc[qg][kb][j] = pv; ps += pv; }
;                 lsum[qg] = lsum[qg] * alpha + ps;
; #pragma unroll
;                 for (int d = 0; d < 8; ++d) oacc[qg][d] *= alpha;
;                 u32x4 w; w.x = cvt_pk_bf16(sacc[qg][0][0], sacc[qg][0][1]); w.y = cvt_pk_bf16(sacc[qg][0][2], sacc[qg][0][3]);
;                 w.z = cvt_pk_bf16(sacc[qg][1][0], sacc[qg][1][1]); w.w = cvt_pk_bf16(sacc[qg][1][2], sacc[qg][1][3]);
dn0_jn1:
	s_waitcnt lgkmcnt(0)
	s_barrier
	ds_read_b128 v[144:147], v240 offset:0
	ds_read_b128 v[148:151], v240 offset:32
	ds_read_b128 v[152:155], v240 offset:64
	ds_read_b128 v[156:159], v240 offset:96
	ds_read_b128 v[160:163], v240 offset:128
	ds_read_b128 v[164:167], v240 offset:160
	v_max3_f32 v193, v128, v129, v130
	v_max3_f32 v192, v131, v132, v133
	v_max3_f32 v193, v193, v134, v135
	v_max3_f32 v192, v192, v136, v137
	v_max3_f32 v193, v193, v138, v139
	v_max3_f32 v192, v192, v140, v141
	v_max3_f32 v193, v193, v142, v143
	v_max_f32_e32 v193, v193, v192
	v_mov_b32_e32 v192, v193
	s_nop 1
	s_waitcnt lgkmcnt(5)
	v_mfma_f32_32x32x16_bf16 v[112:127], v[144:147], v[0:3], 0
	v_permlane32_swap_b32_e32 v193, v192
	v_max_f32_e32 v193, v193, v192
	v_mul_f32_e32 v193, s22, v193
	v_max_f32_e32 v192, v242, v193
	v_sub_f32_e32 v193, v192, v242
	ds_read_b128 v[144:147], v240 offset:192
	s_waitcnt lgkmcnt(5)
	v_mfma_f32_32x32x16_bf16 v[112:127], v[148:151], v[4:7], v[112:127]
	v_cmp_gt_f32_e64 s[68:69], v193, s29
	s_cmp_lg_u64 s[68:69], 0
	s_cselect_b64 s[68:69], -1, 0
	v_cndmask_b32_e64 v192, v242, v192, s[68:69]
	v_sub_f32_e32 v193, v242, v192
	ds_read_b128 v[148:151], v240 offset:224
	s_waitcnt lgkmcnt(5)
	v_mfma_f32_32x32x16_bf16 v[112:127], v[152:155], v[8:11], v[112:127]
	v_exp_f32_e32 v246, v193
	v_mov_b32_e32 v242, v192
	v_pk_fma_f32 v[128:129], v[128:129], v[254:255], v[192:193] op_sel_hi:[1,0,0] neg_lo:[0,0,1] neg_hi:[0,0,1]
	v_pk_fma_f32 v[130:131], v[130:131], v[254:255], v[192:193] op_sel_hi:[1,0,0] neg_lo:[0,0,1] neg_hi:[0,0,1]
	v_pk_fma_f32 v[132:133], v[132:133], v[254:255], v[192:193] op_sel_hi:[1,0,0] neg_lo:[0,0,1] neg_hi:[0,0,1]
	ds_read_b128 v[152:155], v240 offset:256
	s_waitcnt lgkmcnt(5)
	v_mfma_f32_32x32x16_bf16 v[112:127], v[156:159], v[12:15], v[112:127]
	v_pk_fma_f32 v[134:135], v[134:135], v[254:255], v[192:193] op_sel_hi:[1,0,0] neg_lo:[0,0,1] neg_hi:[0,0,1]
	v_pk_fma_f32 v[136:137], v[136:137], v[254:255], v[192:193] op_sel_hi:[1,0,0] neg_lo:[0,0,1] neg_hi:[0,0,1]
	v_pk_fma_f32 v[138:139], v[138:139], v[254:255], v[192:193] op_sel_hi:[1,0,0] neg_lo:[0,0,1] neg_hi:[0,0,1]
	v_pk_fma_f32 v[140:141], v[140:141], v[254:255], v[192:193] op_sel_hi:[1,0,0] neg_lo:[0,0,1] neg_hi:[0,0,1]
	v_pk_fma_f32 v[142:143], v[142:143], v[254:255], v[192:193] op_sel_hi:[1,0,0] neg_lo:[0,0,1] neg_hi:[0,0,1]
	ds_read_b128 v[156:159], v240 offset:288
	s_waitcnt lgkmcnt(5)
	v_mfma_f32_32x32x16_bf16 v[112:127], v[160:163], v[16:19], v[112:127]
	v_exp_f32_e32 v128, v128
	v_exp_f32_e32 v129, v129
	v_exp_f32_e32 v130, v130
	v_exp_f32_e32 v131, v131
	v_exp_f32_e32 v132, v132
	ds_read_b128 v[160:163], v240 offset:320
	s_waitcnt lgkmcnt(5)
	v_mfma_f32_32x32x16_bf16 v[112:127], v[164:167], v[20:23], v[112:127]
	v_exp_f32_e32 v133, v133
	v_exp_f32_e32 v134, v134
	v_exp_f32_e32 v135, v135
	v_exp_f32_e32 v136, v136
	v_exp_f32_e32 v137, v137
	ds_read_b128 v[164:167], v240 offset:352
	s_waitcnt lgkmcnt(5)
	v_mfma_f32_32x32x16_bf16 v[112:127], v[144:147], v[24:27], v[112:127]
	v_exp_f32_e32 v138, v138
	v_exp_f32_e32 v139, v139
	v_exp_f32_e32 v140, v140
	v_exp_f32_e32 v141, v141
	v_exp_f32_e32 v142, v142
	ds_read_b64 v[168:169], v241 offset:64
	ds_read_b64 v[170:171], v241 offset:80
	s_waitcnt lgkmcnt(6)
	v_mfma_f32_32x32x16_bf16 v[112:127], v[148:151], v[28:31], v[112:127]
	v_exp_f32_e32 v143, v143
	v_pk_add_f32 v[196:197], v[128:129], v[130:131]
	v_pk_add_f32 v[198:199], v[132:133], v[134:135]
	v_pk_add_f32 v[196:197], v[196:197], v[136:137]
	v_pk_add_f32 v[198:199], v[198:199], v[138:139]
	ds_read_b64 v[172:173], v241 offset:96
	ds_read_b64 v[174:175], v241 offset:112
	s_waitcnt lgkmcnt(7)
	v_mfma_f32_32x32x16_bf16 v[112:127], v[152:155], v[32:35], v[112:127]
	v_pk_add_f32 v[196:197], v[196:197], v[140:141]
	v_pk_add_f32 v[198:199], v[198:199], v[142:143]
	v_pk_add_f32 v[196:197], v[196:197], v[198:199]
	v_add_f32_e32 v193, v196, v197
	v_fma_f32 v244, v244, v246, v193
	ds_read_b64 v[176:177], v241 offset:4672
	ds_read_b64 v[178:179], v241 offset:4688
	s_waitcnt lgkmcnt(8)
	v_mfma_f32_32x32x16_bf16 v[112:127], v[156:159], v[36:39], v[112:127]
	v_cvt_pk_bf16_f32 v184, v128, v129
	v_cvt_pk_bf16_f32 v185, v130, v131
	v_cvt_pk_bf16_f32 v186, v132, v133
	v_cvt_pk_bf16_f32 v187, v134, v135
	v_cvt_pk_bf16_f32 v188, v136, v137
	ds_read_b64 v[180:181], v241 offset:4704
	ds_read_b64 v[182:183], v241 offset:4720
	s_waitcnt lgkmcnt(9)
	v_mfma_f32_32x32x16_bf16 v[112:127], v[160:163], v[40:43], v[112:127]
	v_cvt_pk_bf16_f32 v189, v138, v139
	v_cvt_pk_bf16_f32 v190, v140, v141
	v_cvt_pk_bf16_f32 v191, v142, v143
	s_waitcnt lgkmcnt(8)
	v_mfma_f32_32x32x16_bf16 v[112:127], v[164:167], v[44:47], v[112:127]
	s_mov_b64 vcc, s[68:69]
	s_cbranch_vccz dn0_nr2
; #define LAS __attribute__((address_space(3)))
; #define MFMA16(a, b, c) __builtin_amdgcn_mfma_f32_16x16x32_bf16((a), (b), (c), 0, 0, 0)
; template <int DK>
; DI void dense_attn_item(LAS unsigned char* lds, const bf16_t* Qb, int ldq, const bf16_t* Kb, int ldk, const bf16_t* Kpe, const bf16_t* Vt, int nkeys, float sl2, bf16_t* Ob) {
;     ...
; #pragma unroll
;             for (int dh = 0; dh < 4; ++dh) {
;                 bf16x8 vfr[2];
; #pragma unroll
;                 for (int d4 = 0; d4 < 2; ++d4) {
;                     const int d = dh * 2 + d4;
;                     const u32x2 lo = *(const LAS u32x2*)(vb_ + (d * 16 + r16) * VROW + (kc * 32 + q4 * 4) * 2);
;                     const u32x2 hi = *(const LAS u32x2*)(vb_ + (d * 16 + r16) * VROW + (kc * 32 + 16 + q4 * 4) * 2);
;                     u32x4 w; w.x = lo.x; w.y = lo.y; w.z = hi.x; w.w = hi.y;
;                     vfr[d4] = __builtin_bit_cast(bf16x8, w);
;                 }
;                 __builtin_amdgcn_s_setprio(1);
; #pragma unroll
;                 for (int d4 = 0; d4 < 2; ++d4) { const int d = dh * 2 + d4; oacc[0][d] = MFMA16(vfr[d4], pb[0], oacc[0][d]); oacc[1][d] = MFMA16(vfr[d4], pb[1], oacc[1][d]); }
;                 __builtin_amdgcn_s_setprio(0);
;             }
;         }
;         if (kt + 1 < ntiles) DA_STORE(cur ^ 1);
	v_pk_mul_f32 v[48:49], v[48:49], v[246:247] op_sel_hi:[1,0]
	v_pk_mul_f32 v[50:51], v[50:51], v[246:247] op_sel_hi:[1,0]
	v_pk_mul_f32 v[52:53], v[52:53], v[246:247] op_sel_hi:[1,0]
	v_pk_mul_f32 v[54:55], v[54:55], v[246:247] op_sel_hi:[1,0]
	v_pk_mul_f32 v[56:57], v[56:57], v[246:247] op_sel_hi:[1,0]
	v_pk_mul_f32 v[58:59], v[58:59], v[246:247] op_sel_hi:[1,0]
	v_pk_mul_f32 v[60:61], v[60:61], v[246:247] op_sel_hi:[1,0]
	v_pk_mul_f32 v[62:63], v[62:63], v[246:247] op_sel_hi:[1,0]
	s_waitcnt lgkmcnt(6)
	v_mfma_f32_32x32x16_bf16 v[48:63], v[168:171], v[184:187], v[48:63]
	v_pk_mul_f32 v[64:65], v[64:65], v[246:247] op_sel_hi:[1,0]
	v_pk_mul_f32 v[66:67], v[66:67], v[246:247] op_sel_hi:[1,0]
	v_pk_mul_f32 v[68:69], v[68:69], v[246:247] op_sel_hi:[1,0]
	v_pk_mul_f32 v[70:71], v[70:71], v[246:247] op_sel_hi:[1,0]
	ds_read_b64 v[168:169], v241 offset:9280
	ds_read_b64 v[170:171], v241 offset:9296
	s_waitcnt lgkmcnt(6)
	v_mfma_f32_32x32x16_bf16 v[48:63], v[172:175], v[188:191], v[48:63]
	v_pk_mul_f32 v[72:73], v[72:73], v[246:247] op_sel_hi:[1,0]
	v_pk_mul_f32 v[74:75], v[74:75], v[246:247] op_sel_hi:[1,0]
	v_pk_mul_f32 v[76:77], v[76:77], v[246:247] op_sel_hi:[1,0]
	v_pk_mul_f32 v[78:79], v[78:79], v[246:247] op_sel_hi:[1,0]
	ds_read_b64 v[172:173], v241 offset:9312
	ds_read_b64 v[174:175], v241 offset:9328
	s_waitcnt lgkmcnt(6)
	v_mfma_f32_32x32x16_bf16 v[64:79], v[176:179], v[184:187], v[64:79]
	v_pk_mul_f32 v[80:81], v[80:81], v[246:247] op_sel_hi:[1,0]
	v_pk_mul_f32 v[82:83], v[82:83], v[246:247] op_sel_hi:[1,0]
	v_pk_mul_f32 v[84:85], v[84:85], v[246:247] op_sel_hi:[1,0]
	v_pk_mul_f32 v[86:87], v[86:87], v[246:247] op_sel_hi:[1,0]
	ds_read_b64 v[176:177], v241 offset:13888
	ds_read_b64 v[178:179], v241 offset:13904
	ds_read_b128 v[144:147], v240 offset:12800
	s_waitcnt lgkmcnt(7)
	v_mfma_f32_32x32x16_bf16 v[64:79], v[180:183], v[188:191], v[64:79]
	v_pk_mul_f32 v[88:89], v[88:89], v[246:247] op_sel_hi:[1,0]
	v_pk_mul_f32 v[90:91], v[90:91], v[246:247] op_sel_hi:[1,0]
	v_pk_mul_f32 v[92:93], v[92:93], v[246:247] op_sel_hi:[1,0]
	v_pk_mul_f32 v[94:95], v[94:95], v[246:247] op_sel_hi:[1,0]
	ds_read_b64 v[180:181], v241 offset:13920
	ds_read_b64 v[182:183], v241 offset:13936
	ds_read_b128 v[148:151], v240 offset:12832
	s_waitcnt lgkmcnt(8)
	v_mfma_f32_32x32x16_bf16 v[80:95], v[168:171], v[184:187], v[80:95]
	v_pk_mul_f32 v[96:97], v[96:97], v[246:247] op_sel_hi:[1,0]
	v_pk_mul_f32 v[98:99], v[98:99], v[246:247] op_sel_hi:[1,0]
	v_pk_mul_f32 v[100:101], v[100:101], v[246:247] op_sel_hi:[1,0]
	v_pk_mul_f32 v[102:103], v[102:103], v[246:247] op_sel_hi:[1,0]
	s_nop 1
	ds_read_b128 v[152:155], v240 offset:12864
	s_waitcnt lgkmcnt(7)
	v_mfma_f32_32x32x16_bf16 v[80:95], v[172:175], v[188:191], v[80:95]
	v_pk_mul_f32 v[104:105], v[104:105], v[246:247] op_sel_hi:[1,0]
	v_pk_mul_f32 v[106:107], v[106:107], v[246:247] op_sel_hi:[1,0]
	v_pk_mul_f32 v[108:109], v[108:109], v[246:247] op_sel_hi:[1,0]
	v_pk_mul_f32 v[110:111], v[110:111], v[246:247] op_sel_hi:[1,0]
	s_nop 1
	ds_read_b128 v[156:159], v240 offset:12896
	s_waitcnt lgkmcnt(6)
	v_mfma_f32_32x32x16_bf16 v[96:111], v[176:179], v[184:187], v[96:111]
	ds_read_b128 v[160:163], v240 offset:12928
	s_waitcnt lgkmcnt(4)
	v_mfma_f32_32x32x16_bf16 v[96:111], v[180:183], v[188:191], v[96:111]
	ds_read_b128 v[164:167], v240 offset:12960
	s_branch dn0_jn2
dn0_nr2:
	s_nop 1
	s_waitcnt lgkmcnt(6)
	v_mfma_f32_32x32x16_bf16 v[48:63], v[168:171], v[184:187], v[48:63]
	ds_read_b64 v[168:169], v241 offset:9280
	ds_read_b64 v[170:171], v241 offset:9296
	s_waitcnt lgkmcnt(6)
	v_mfma_f32_32x32x16_bf16 v[48:63], v[172:175], v[188:191], v[48:63]
	ds_read_b64 v[172:173], v241 offset:9312
	ds_read_b64 v[174:175], v241 offset:9328
	s_waitcnt lgkmcnt(6)
	v_mfma_f32_32x32x16_bf16 v[64:79], v[176:179], v[184:187], v[64:79]
	ds_read_b64 v[176:177], v241 offset:13888
	ds_read_b64 v[178:179], v241 offset:13904
	ds_read_b128 v[144:147], v240 offset:12800
	s_waitcnt lgkmcnt(7)
	v_mfma_f32_32x32x16_bf16 v[64:79], v[180:183], v[188:191], v[64:79]
	ds_read_b64 v[180:181], v241 offset:13920
	ds_read_b64 v[182:183], v241 offset:13936
	ds_read_b128 v[148:151], v240 offset:12832
	s_waitcnt lgkmcnt(8)
	v_mfma_f32_32x32x16_bf16 v[80:95], v[168:171], v[184:187], v[80:95]
	ds_read_b128 v[152:155], v240 offset:12864
	s_waitcnt lgkmcnt(7)
	v_mfma_f32_32x32x16_bf16 v[80:95], v[172:175], v[188:191], v[80:95]
	ds_read_b128 v[156:159], v240 offset:12896
	s_waitcnt lgkmcnt(6)
	v_mfma_f32_32x32x16_bf16 v[96:111], v[176:179], v[184:187], v[96:111]
	ds_read_b128 v[160:163], v240 offset:12928
	s_waitcnt lgkmcnt(4)
	v_mfma_f32_32x32x16_bf16 v[96:111], v[180:183], v[188:191], v[96:111]
	ds_read_b128 v[164:167], v240 offset:12960

; #define LAS __attribute__((address_space(3)))
; DI int otid() { int t = threadIdx.x; asm volatile("" : "+v"(t)); return t; }
; template <int DK>
; DI void dense_attn_item(LAS unsigned char* lds, const bf16_t* Qb, int ldq, const bf16_t* Kb, int ldk, const bf16_t* Kpe, const bf16_t* Vt, int nkeys, float sl2, bf16_t* Ob) {
;     const int tid = otid(), lane = tid & 63, wid = tid >> 6, r16 = lane & 15, q4 = lane >> 4;
;     constexpr int KS = DK / 32, KCH = DK / 8, KROW = DK * 2 + 16, KTILE = 64 * KROW, VROW = 144, VTILE = 128 * VROW, NKL = (64 * KCH) / 512;
;     bf16x8 qf[2][KS];
; #pragma unroll
;     for (int qg = 0; qg < 2; ++qg)
; #pragma unroll
;         for (int ks = 0; ks < KS; ++ks) qf[qg][ks] = *(const bf16x8*)(Qb + (size_t)(wid * 32 + qg * 16 + r16) * ldq + ks * 32 + q4 * 8);
;     f32x4 oacc[2][8];
; #pragma unroll
;     for (int qg = 0; qg < 2; ++qg)
; #pragma unroll
;         for (int d = 0; d < 8; ++d) oacc[qg][d] = (f32x4){0.f, 0.f, 0.f, 0.f};
;     float mrun[2] = {-1e30f, -1e30f}, lsum[2] = {0.f, 0.f};
;     u32x4 kst[NKL], vst[2];
;     const int ntiles = nkeys >> 6;
;     ...
;     DA_LOAD(0); DA_STORE(0);
;     __syncthreads();
; DI void dense192_item(unsigned char* ws, LAS unsigned char* lds, int b, int h, int q0, int nk) {
;     const size_t rowb = (size_t)b * RB, row0 = rowb + q0;
;     dense_attn_item<192>(lds, (const bf16_t*)(ws + WS_QM) + row0 * 960 + h * 192, 960, (const bf16_t*)(ws + WS_KM) + rowb * 640 + h * 128, 640, (const bf16_t*)(ws + WS_KPE) + rowb * 64,
;                          (const bf16_t*)(ws + WS_VTM) + ((size_t)b * 640 + h * 128) * RB, nk, 0.07216878364870322f * 1.4426950408889634f, (bf16_t*)(ws + WS_YMIX) + row0 * DM + 768 + h * 128);
.LBB0_2593:
	s_mul_hi_u32 s71, s0, 0x66666667
	s_lshr_b32 s71, s71, 4
	s_lshr_b32 s73, s0, 3
	s_mul_i32 s62, s71, 5
	s_sub_u32 s73, s73, s62
	s_and_b32 s62, s0, 7
	s_lshl_b32 s62, s62, 8
	s_mul_i32 s75, s71, 0x900
	s_add_u32 s74, s75, s62
	s_addk_i32 s74, 0x100
	s_mul_i32 s62, s74, 0x780
	s_mul_i32 s63, s73, 0x180
	s_add_u32 s62, s62, s63
	s_add_u32 s62, s62, 0x1a3a0000
	s_add_u32 s10, s50, s62
	s_addc_u32 s11, s51, 0
	s_mul_i32 s62, s75, 0x500
	s_lshl_b32 s63, s73, 8
	s_add_u32 s62, s62, s63
	s_add_u32 s62, s62, 0x1b480000
	s_add_u32 s4, s50, s62
	s_addc_u32 s5, s51, 0
	s_mul_i32 s62, s75, 0x480
	s_add_u32 s62, s62, s63
	s_sub_u32 s76, 0x167ff00, s62
	s_mul_i32 s62, s71, 0x280
	s_lshl_b32 s63, s73, 7
	s_add_u32 s62, s62, s63
	s_mul_i32 s62, s62, 0x1200
	s_add_u32 s62, s62, 0x1bfc0000
	s_add_u32 s8, s50, s62
	s_addc_u32 s9, s51, 0
	s_lshl_b32 s62, s74, 12
	s_lshl_b32 s63, s73, 8
	s_add_u32 s62, s62, s63
	s_add_u32 s62, s62, 0x1d9a0600
	s_add_u32 s20, s50, s62
	s_addc_u32 s21, s51, 0
	s_mov_b32 s22, 0x3dd53b94
	v_mov_b32_e32 v254, s22
	s_mov_b32 s29, 0x41000000
	v_and_b32_e32 v192, 31, v202
	v_bfe_u32 v193, v202, 5, 1
	v_lshrrev_b32_e32 v194, 6, v202
	v_lshl_add_u32 v195, v194, 5, v192
	v_mul_u32_u24_e32 v196, 0x780, v195
	v_lshl_add_u32 v250, v193, 4, v196
	global_load_dwordx4 v[0:3], v250, s[10:11] offset:0
	global_load_dwordx4 v[4:7], v250, s[10:11] offset:32
	global_load_dwordx4 v[8:11], v250, s[10:11] offset:64
	global_load_dwordx4 v[12:15], v250, s[10:11] offset:96
	global_load_dwordx4 v[16:19], v250, s[10:11] offset:128
	global_load_dwordx4 v[20:23], v250, s[10:11] offset:160
	global_load_dwordx4 v[24:27], v250, s[10:11] offset:192
	global_load_dwordx4 v[28:31], v250, s[10:11] offset:224
	global_load_dwordx4 v[32:35], v250, s[10:11] offset:256
	global_load_dwordx4 v[36:39], v250, s[10:11] offset:288
	global_load_dwordx4 v[40:43], v250, s[10:11] offset:320
	global_load_dwordx4 v[44:47], v250, s[10:11] offset:352
	s_mov_b32 s62, 0xaaaaaab
	v_mov_b32_e32 v197, v202
	v_mul_hi_u32 v198, v197, s62
	v_mul_u32_u24_e32 v195, 24, v198
	v_sub_u32_e32 v199, v197, v195
	v_mul_u32_u24_e32 v195, 0x190, v198
	v_lshl_add_u32 v230, v199, 4, v195
	v_cmp_gt_u32_e32 vcc, 16, v199
	v_mul_u32_u24_e32 v195, 0x500, v198
	v_lshlrev_b32_e32 v196, 7, v198
	v_add_u32_e32 v196, s76, v196
	s_nop 1
	v_cndmask_b32_e32 v195, v196, v195, vcc
	v_lshl_add_u32 v224, v199, 4, v195
	v_mov_b32_e32 v195, 0x2000
	v_mov_b32_e32 v196, 0x14000
	v_cndmask_b32_e32 v227, v195, v196, vcc
	v_add_u32_e32 v197, 0x200, v202
	v_mul_hi_u32 v198, v197, s62
	v_mul_u32_u24_e32 v195, 24, v198
	v_sub_u32_e32 v199, v197, v195
	v_mul_u32_u24_e32 v195, 0x190, v198
	v_lshl_add_u32 v231, v199, 4, v195
	v_cmp_gt_u32_e32 vcc, 16, v199
	v_mul_u32_u24_e32 v195, 0x500, v198
	v_lshlrev_b32_e32 v196, 7, v198
	v_add_u32_e32 v196, s76, v196
	s_nop 1
	v_cndmask_b32_e32 v195, v196, v195, vcc
	v_lshl_add_u32 v225, v199, 4, v195
	v_mov_b32_e32 v195, 0x2000
	v_mov_b32_e32 v196, 0x14000
	v_cndmask_b32_e32 v228, v195, v196, vcc
	v_add_u32_e32 v197, 0x400, v202
	v_mul_hi_u32 v198, v197, s62
	v_mul_u32_u24_e32 v195, 24, v198
	v_sub_u32_e32 v199, v197, v195
	v_mul_u32_u24_e32 v195, 0x190, v198
	v_lshl_add_u32 v232, v199, 4, v195
	v_cmp_gt_u32_e32 vcc, 16, v199
	v_mul_u32_u24_e32 v195, 0x500, v198
	v_lshlrev_b32_e32 v196, 7, v198
	v_add_u32_e32 v196, s76, v196
	s_nop 1
	v_cndmask_b32_e32 v195, v196, v195, vcc
	v_lshl_add_u32 v226, v199, 4, v195
	v_mov_b32_e32 v195, 0x2000
	v_mov_b32_e32 v196, 0x14000
	v_cndmask_b32_e32 v229, v195, v196, vcc
	v_mov_b32_e32 v197, v202
	v_lshrrev_b32_e32 v198, 3, v197
	v_and_b32_e32 v199, 7, v197
	v_mul_u32_u24_e32 v195, 0x1200, v198
	v_lshl_add_u32 v233, v199, 4, v195
	v_mul_u32_u24_e32 v195, 0x90, v198
	v_lshl_add_u32 v195, v199, 4, v195
	v_add_u32_e32 v235, 0x12c00, v195
	v_add_u32_e32 v197, 0x200, v202
	v_lshrrev_b32_e32 v198, 3, v197
	v_and_b32_e32 v199, 7, v197
	v_mul_u32_u24_e32 v195, 0x1200, v198
	v_lshl_add_u32 v234, v199, 4, v195
	v_mul_u32_u24_e32 v195, 0x90, v198
	v_lshl_add_u32 v195, v199, 4, v195
	v_add_u32_e32 v236, 0x12c00, v195
	v_mul_u32_u24_e32 v195, 0x190, v192
	v_lshl_add_u32 v237, v193, 4, v195
	v_mul_u32_u24_e32 v195, 0x90, v192
	v_lshl_add_u32 v195, v193, 3, v195
	v_add_u32_e32 v238, 0x12c00, v195
	global_load_dwordx4 v[204:207], v224, s[4:5]
	global_load_dwordx4 v[208:211], v225, s[4:5]
	global_load_dwordx4 v[212:215], v226, s[4:5]
	global_load_dwordx4 v[216:219], v233, s[8:9]
	global_load_dwordx4 v[220:223], v234, s[8:9]
	v_add_u32_e32 v224, v224, v227
	v_add_u32_e32 v225, v225, v228
	v_add_u32_e32 v226, v226, v229
	s_add_u32 s8, s8, 0x80
	s_addc_u32 s9, s9, 0
	v_mov_b32_e32 v48, 0
	v_mov_b32_e32 v49, 0
	v_mov_b32_e32 v50, 0
	v_mov_b32_e32 v51, 0
	v_mov_b32_e32 v52, 0
	v_mov_b32_e32 v53, 0
	v_mov_b32_e32 v54, 0
	v_mov_b32_e32 v55, 0
	v_mov_b32_e32 v56, 0
	v_mov_b32_e32 v57, 0
	v_mov_b32_e32 v58, 0
	v_mov_b32_e32 v59, 0
	v_mov_b32_e32 v60, 0
	v_mov_b32_e32 v61, 0
	v_mov_b32_e32 v62, 0
	v_mov_b32_e32 v63, 0
	v_mov_b32_e32 v64, 0
	v_mov_b32_e32 v65, 0
	v_mov_b32_e32 v66, 0
	v_mov_b32_e32 v67, 0
	v_mov_b32_e32 v68, 0
	v_mov_b32_e32 v69, 0
	v_mov_b32_e32 v70, 0
	v_mov_b32_e32 v71, 0
	v_mov_b32_e32 v72, 0
	v_mov_b32_e32 v73, 0
	v_mov_b32_e32 v74, 0
	v_mov_b32_e32 v75, 0
	v_mov_b32_e32 v76, 0
	v_mov_b32_e32 v77, 0
	v_mov_b32_e32 v78, 0
	v_mov_b32_e32 v79, 0
	v_mov_b32_e32 v80, 0
	v_mov_b32_e32 v81, 0
	v_mov_b32_e32 v82, 0
	v_mov_b32_e32 v83, 0
	v_mov_b32_e32 v84, 0
	v_mov_b32_e32 v85, 0
	v_mov_b32_e32 v86, 0
	v_mov_b32_e32 v87, 0
	v_mov_b32_e32 v88, 0
	v_mov_b32_e32 v89, 0
	v_mov_b32_e32 v90, 0
	v_mov_b32_e32 v91, 0
	v_mov_b32_e32 v92, 0
	v_mov_b32_e32 v93, 0
	v_mov_b32_e32 v94, 0
	v_mov_b32_e32 v95, 0
	v_mov_b32_e32 v96, 0
	v_mov_b32_e32 v97, 0
	v_mov_b32_e32 v98, 0
	v_mov_b32_e32 v99, 0
	v_mov_b32_e32 v100, 0
	v_mov_b32_e32 v101, 0
	v_mov_b32_e32 v102, 0
	v_mov_b32_e32 v103, 0
	v_mov_b32_e32 v104, 0
	v_mov_b32_e32 v105, 0
	v_mov_b32_e32 v106, 0
	v_mov_b32_e32 v107, 0
	v_mov_b32_e32 v108, 0
	v_mov_b32_e32 v109, 0
	v_mov_b32_e32 v110, 0
	v_mov_b32_e32 v111, 0
	v_mov_b32_e32 v242, 0xf149f2ca
	v_mov_b32_e32 v244, 0
	s_waitcnt vmcnt(0)
	v_lshl_add_u32 v195, v194, 5, v192
	v_lshlrev_b32_e32 v195, 12, v195
	v_lshl_add_u32 v250, v193, 3, v195
	ds_write_b128 v230, v[204:207]
	ds_write_b128 v231, v[208:211]
	ds_write_b128 v232, v[212:215]
	ds_write_b128 v235, v[216:219]
	ds_write_b128 v236, v[220:223]
	s_waitcnt lgkmcnt(0)
	global_load_dwordx4 v[204:207], v224, s[4:5]
	global_load_dwordx4 v[208:211], v225, s[4:5]
	global_load_dwordx4 v[212:215], v226, s[4:5]
	global_load_dwordx4 v[216:219], v233, s[8:9]
	global_load_dwordx4 v[220:223], v234, s[8:9]
	s_barrier
; template <int DK>
; DI void dense_attn_item(LAS unsigned char* lds, const bf16_t* Qb, int ldq, const bf16_t* Kb, int ldk, const bf16_t* Kpe, const bf16_t* Vt, int nkeys, float sl2, bf16_t* Ob) {
;     ...
;     for (int kt = 0; kt < ntiles; ++kt) {
;         const int cur = kt & 1;
;         if (kt + 1 < ntiles) DA_LOAD((kt + 1) * 64);
;         const LAS unsigned char* kb_ = lds + cur * KTILE; const LAS unsigned char* vb_ = lds + 2 * KTILE + cur * VTILE;
; #pragma unroll
;         for (int kc = 0; kc < 2; ++kc) {
;             f32x4 sacc[2][2];
; #pragma unroll
;             for (int kb = 0; kb < 2; ++kb) {
;                 sacc[0][kb] = (f32x4){0.f, 0.f, 0.f, 0.f}; sacc[1][kb] = (f32x4){0.f, 0.f, 0.f, 0.f};
; #pragma unroll
;                 for (int kh = 0; kh < KS / 2; ++kh) {
;                     const bf16x8 k0 = *(const LAS bf16x8*)(kb_ + ((2 * kc + kb) * 16 + r16) * KROW + (2 * kh) * 64 + q4 * 16);
;                     const bf16x8 k1 = *(const LAS bf16x8*)(kb_ + ((2 * kc + kb) * 16 + r16) * KROW + (2 * kh + 1) * 64 + q4 * 16);
;                     __builtin_amdgcn_s_setprio(1);
;                     sacc[0][kb] = MFMA16(k0, qf[0][2 * kh], sacc[0][kb]); sacc[1][kb] = MFMA16(k0, qf[1][2 * kh], sacc[1][kb]);
;                     sacc[0][kb] = MFMA16(k1, qf[0][2 * kh + 1], sacc[0][kb]); sacc[1][kb] = MFMA16(k1, qf[1][2 * kh + 1], sacc[1][kb]);
;                     __builtin_amdgcn_s_setprio(0);
;                 }
;             }
;             bf16x8 pb[2];
; #pragma unroll
;             for (int qg = 0; qg < 2; ++qg) {
;                 float mx = fmaxf(fmaxf(fmaxf(sacc[qg][0][0], sacc[qg][0][1]), fmaxf(sacc[qg][0][2], sacc[qg][0][3])), fmaxf(fmaxf(sacc[qg][1][0], sacc[qg][1][1]), fmaxf(sacc[qg][1][2], sacc[qg][1][3])));
;                 mx = fmaxf(mx, __shfl_xor(mx, 16)); mx = fmaxf(mx, __shfl_xor(mx, 32));
;                 const float mnew = fmaxf(mrun[qg], mx * sl2), alpha = fast_exp2(mrun[qg] - mnew);
;                 mrun[qg] = mnew;
;                 float ps = 0.f;
; #pragma unroll
;                 for (int kb = 0; kb < 2; ++kb)
; #pragma unroll
;                     for (int j = 0; j < 4; ++j) { const float pv = fast_exp2(sacc[qg][kb][j] * sl2 - mnew); sacc[qg][kb][j] = pv; ps += pv; }
;                 lsum[qg] = lsum[qg] * alpha + ps;
; #pragma unroll
;                 for (int d = 0; d < 8; ++d) oacc[qg][d] *= alpha;
	v_mov_b32_e32 v239, v237
	ds_read_b128 v[144:147], v239 offset:0
	ds_read_b128 v[148:151], v239 offset:32
	ds_read_b128 v[152:155], v239 offset:64
	ds_read_b128 v[156:159], v239 offset:96
	ds_read_b128 v[160:163], v239 offset:128
	ds_read_b128 v[164:167], v239 offset:160
	s_waitcnt lgkmcnt(5)
	v_mfma_f32_32x32x16_bf16 v[112:127], v[144:147], v[0:3], 0
	ds_read_b128 v[144:147], v239 offset:192
	s_waitcnt lgkmcnt(5)
	v_mfma_f32_32x32x16_bf16 v[112:127], v[148:151], v[4:7], v[112:127]
	ds_read_b128 v[148:151], v239 offset:224
	s_waitcnt lgkmcnt(5)
	v_mfma_f32_32x32x16_bf16 v[112:127], v[152:155], v[8:11], v[112:127]
	ds_read_b128 v[152:155], v239 offset:256
	s_waitcnt lgkmcnt(5)
	v_mfma_f32_32x32x16_bf16 v[112:127], v[156:159], v[12:15], v[112:127]
	ds_read_b128 v[156:159], v239 offset:288
	s_waitcnt lgkmcnt(5)
	v_mfma_f32_32x32x16_bf16 v[112:127], v[160:163], v[16:19], v[112:127]
	ds_read_b128 v[160:163], v239 offset:320
	s_waitcnt lgkmcnt(5)
	v_mfma_f32_32x32x16_bf16 v[112:127], v[164:167], v[20:23], v[112:127]
	ds_read_b128 v[164:167], v239 offset:352
	s_waitcnt lgkmcnt(5)
	v_mfma_f32_32x32x16_bf16 v[112:127], v[144:147], v[24:27], v[112:127]
	s_waitcnt lgkmcnt(4)
	v_mfma_f32_32x32x16_bf16 v[112:127], v[148:151], v[28:31], v[112:127]
	s_waitcnt lgkmcnt(3)
	v_mfma_f32_32x32x16_bf16 v[112:127], v[152:155], v[32:35], v[112:127]
	s_waitcnt lgkmcnt(2)
	v_mfma_f32_32x32x16_bf16 v[112:127], v[156:159], v[36:39], v[112:127]
	s_waitcnt lgkmcnt(1)
	v_mfma_f32_32x32x16_bf16 v[112:127], v[160:163], v[40:43], v[112:127]
	s_waitcnt lgkmcnt(0)
	v_mfma_f32_32x32x16_bf16 v[112:127], v[164:167], v[44:47], v[112:127]
	ds_read_b128 v[144:147], v239 offset:12800
	ds_read_b128 v[148:151], v239 offset:12832
	ds_read_b128 v[152:155], v239 offset:12864
	ds_read_b128 v[156:159], v239 offset:12896
	ds_read_b128 v[160:163], v239 offset:12928
	ds_read_b128 v[164:167], v239 offset:12960
	s_mov_b32 s23, 0
	s_mov_b32 s27, 0
dn1_top:
	s_add_u32 s57, s27, 1
	s_cmp_eq_u32 s57, 3
	s_cselect_b32 s57, 0, s57
	s_mul_i32 s36, s27, 0x6400
	s_mul_i32 s54, s27, 0x4800
	s_mul_i32 s37, s57, 0x6400
	s_mul_i32 s56, s57, 0x4800
	v_add_u32_e32 v239, s36, v237
	v_add_u32_e32 v240, s37, v237
	v_add_u32_e32 v241, s54, v238
	v_add_u32_e32 v224, v224, v227
	v_add_u32_e32 v225, v225, v228
	v_add_u32_e32 v226, v226, v229
	s_add_u32 s8, s8, 0x80
	s_addc_u32 s9, s9, 0
	v_max3_f32 v193, v112, v113, v114
	v_max3_f32 v192, v115, v116, v117
	v_max3_f32 v193, v193, v118, v119
	v_max3_f32 v192, v192, v120, v121
	s_waitcnt lgkmcnt(5)
	v_mfma_f32_32x32x16_bf16 v[128:143], v[144:147], v[0:3], 0
	v_max3_f32 v193, v193, v122, v123
	v_max3_f32 v192, v192, v124, v125
	v_max3_f32 v193, v193, v126, v127
	v_max_f32_e32 v193, v193, v192
	v_mov_b32_e32 v192, v193
	ds_read_b128 v[144:147], v239 offset:12992
	s_waitcnt lgkmcnt(5)
	v_mfma_f32_32x32x16_bf16 v[128:143], v[148:151], v[4:7], v[128:143]
	s_nop 1
	v_permlane32_swap_b32_e32 v193, v192
	v_max_f32_e32 v193, v193, v192
	v_mul_f32_e32 v193, s22, v193
	v_max_f32_e32 v192, v242, v193
	ds_read_b128 v[148:151], v239 offset:13024
	s_waitcnt lgkmcnt(5)
	v_mfma_f32_32x32x16_bf16 v[128:143], v[152:155], v[8:11], v[128:143]
	v_sub_f32_e32 v193, v192, v242
	v_cmp_gt_f32_e64 s[68:69], v193, s29
	s_cmp_lg_u64 s[68:69], 0
	s_cselect_b64 s[68:69], -1, 0
	v_cndmask_b32_e64 v192, v242, v192, s[68:69]
	ds_read_b128 v[152:155], v239 offset:13056
	s_waitcnt lgkmcnt(5)
	v_mfma_f32_32x32x16_bf16 v[128:143], v[156:159], v[12:15], v[128:143]
	v_sub_f32_e32 v193, v242, v192
	v_exp_f32_e32 v246, v193
	v_mov_b32_e32 v242, v192
	v_pk_fma_f32 v[112:113], v[112:113], v[254:255], v[192:193] op_sel_hi:[1,0,0] neg_lo:[0,0,1] neg_hi:[0,0,1]
	v_pk_fma_f32 v[114:115], v[114:115], v[254:255], v[192:193] op_sel_hi:[1,0,0] neg_lo:[0,0,1] neg_hi:[0,0,1]
	ds_read_b128 v[156:159], v239 offset:13088
	s_waitcnt lgkmcnt(5)
	v_mfma_f32_32x32x16_bf16 v[128:143], v[160:163], v[16:19], v[128:143]
	v_pk_fma_f32 v[116:117], v[116:117], v[254:255], v[192:193] op_sel_hi:[1,0,0] neg_lo:[0,0,1] neg_hi:[0,0,1]
	v_pk_fma_f32 v[118:119], v[118:119], v[254:255], v[192:193] op_sel_hi:[1,0,0] neg_lo:[0,0,1] neg_hi:[0,0,1]
	v_pk_fma_f32 v[120:121], v[120:121], v[254:255], v[192:193] op_sel_hi:[1,0,0] neg_lo:[0,0,1] neg_hi:[0,0,1]
	v_pk_fma_f32 v[122:123], v[122:123], v[254:255], v[192:193] op_sel_hi:[1,0,0] neg_lo:[0,0,1] neg_hi:[0,0,1]
	v_pk_fma_f32 v[124:125], v[124:125], v[254:255], v[192:193] op_sel_hi:[1,0,0] neg_lo:[0,0,1] neg_hi:[0,0,1]
	ds_read_b128 v[160:163], v239 offset:13120
	s_waitcnt lgkmcnt(5)
	v_mfma_f32_32x32x16_bf16 v[128:143], v[164:167], v[20:23], v[128:143]
	v_pk_fma_f32 v[126:127], v[126:127], v[254:255], v[192:193] op_sel_hi:[1,0,0] neg_lo:[0,0,1] neg_hi:[0,0,1]
	v_exp_f32_e32 v112, v112
	v_exp_f32_e32 v113, v113
	v_exp_f32_e32 v114, v114
	v_exp_f32_e32 v115, v115
	ds_read_b128 v[164:167], v239 offset:13152
	s_waitcnt lgkmcnt(5)
	v_mfma_f32_32x32x16_bf16 v[128:143], v[144:147], v[24:27], v[128:143]
	v_exp_f32_e32 v116, v116
	v_exp_f32_e32 v117, v117
	v_exp_f32_e32 v118, v118
	v_exp_f32_e32 v119, v119
	v_exp_f32_e32 v120, v120
	ds_read_b64 v[168:169], v241 offset:0
	ds_read_b64 v[170:171], v241 offset:16
	s_waitcnt lgkmcnt(6)
	v_mfma_f32_32x32x16_bf16 v[128:143], v[148:151], v[28:31], v[128:143]
	v_exp_f32_e32 v121, v121
	v_exp_f32_e32 v122, v122
	v_exp_f32_e32 v123, v123
	v_exp_f32_e32 v124, v124
	v_exp_f32_e32 v125, v125
	ds_read_b64 v[172:173], v241 offset:32
	ds_read_b64 v[174:175], v241 offset:48
	s_waitcnt lgkmcnt(7)
	v_mfma_f32_32x32x16_bf16 v[128:143], v[152:155], v[32:35], v[128:143]
	v_exp_f32_e32 v126, v126
	v_exp_f32_e32 v127, v127
	v_pk_add_f32 v[196:197], v[112:113], v[114:115]
	v_pk_add_f32 v[198:199], v[116:117], v[118:119]
	v_pk_add_f32 v[196:197], v[196:197], v[120:121]
	ds_read_b64 v[176:177], v241 offset:4608
	ds_read_b64 v[178:179], v241 offset:4624
	s_waitcnt lgkmcnt(8)
	v_mfma_f32_32x32x16_bf16 v[128:143], v[156:159], v[36:39], v[128:143]
	v_pk_add_f32 v[198:199], v[198:199], v[122:123]
	v_pk_add_f32 v[196:197], v[196:197], v[124:125]
	v_pk_add_f32 v[198:199], v[198:199], v[126:127]
	v_pk_add_f32 v[196:197], v[196:197], v[198:199]
	v_add_f32_e32 v193, v196, v197
	ds_read_b64 v[180:181], v241 offset:4640
	ds_read_b64 v[182:183], v241 offset:4656
	s_waitcnt lgkmcnt(9)
	v_mfma_f32_32x32x16_bf16 v[128:143], v[160:163], v[40:43], v[128:143]
	v_fma_f32 v244, v244, v246, v193
	v_cvt_pk_bf16_f32 v184, v112, v113
	v_cvt_pk_bf16_f32 v185, v114, v115
	v_cvt_pk_bf16_f32 v186, v116, v117
	v_cvt_pk_bf16_f32 v187, v118, v119
	s_waitcnt lgkmcnt(8)
	v_mfma_f32_32x32x16_bf16 v[128:143], v[164:167], v[44:47], v[128:143]
	v_cvt_pk_bf16_f32 v188, v120, v121
	v_cvt_pk_bf16_f32 v189, v122, v123
	v_cvt_pk_bf16_f32 v190, v124, v125
	v_cvt_pk_bf16_f32 v191, v126, v127
	s_mov_b64 vcc, s[68:69]
	s_cbranch_vccz dn1_nr1
; #define LAS __attribute__((address_space(3)))
; DI unsigned cvt_pk_bf16(float lo, float hi) { unsigned r; asm volatile("v_cvt_pk_bf16_f32 %0, %1, %2" : "=v"(r) : "v"(lo), "v"(hi)); return r; }
; #define MFMA16(a, b, c) __builtin_amdgcn_mfma_f32_16x16x32_bf16((a), (b), (c), 0, 0, 0)
; template <int DK>
; DI void dense_attn_item(LAS unsigned char* lds, const bf16_t* Qb, int ldq, const bf16_t* Kb, int ldk, const bf16_t* Kpe, const bf16_t* Vt, int nkeys, float sl2, bf16_t* Ob) {
;     ...
;                 for (int d = 0; d < 8; ++d) oacc[qg][d] *= alpha;
;                 u32x4 w; w.x = cvt_pk_bf16(sacc[qg][0][0], sacc[qg][0][1]); w.y = cvt_pk_bf16(sacc[qg][0][2], sacc[qg][0][3]);
;                 w.z = cvt_pk_bf16(sacc[qg][1][0], sacc[qg][1][1]); w.w = cvt_pk_bf16(sacc[qg][1][2], sacc[qg][1][3]);
;                 pb[qg] = __builtin_bit_cast(bf16x8, w);
;             }
; #pragma unroll
;             for (int dh = 0; dh < 4; ++dh) {
;                 bf16x8 vfr[2];
; #pragma unroll
;                 for (int d4 = 0; d4 < 2; ++d4) {
;                     const int d = dh * 2 + d4;
;                     const u32x2 lo = *(const LAS u32x2*)(vb_ + (d * 16 + r16) * VROW + (kc * 32 + q4 * 4) * 2);
;                     const u32x2 hi = *(const LAS u32x2*)(vb_ + (d * 16 + r16) * VROW + (kc * 32 + 16 + q4 * 4) * 2);
;                     u32x4 w; w.x = lo.x; w.y = lo.y; w.z = hi.x; w.w = hi.y;
;                     vfr[d4] = __builtin_bit_cast(bf16x8, w);
;                 }
;                 __builtin_amdgcn_s_setprio(1);
; #pragma unroll
;                 for (int d4 = 0; d4 < 2; ++d4) { const int d = dh * 2 + d4; oacc[0][d] = MFMA16(vfr[d4], pb[0], oacc[0][d]); oacc[1][d] = MFMA16(vfr[d4], pb[1], oacc[1][d]); }
;                 __builtin_amdgcn_s_setprio(0);
;             }
;         }
;         if (kt + 1 < ntiles) DA_STORE(cur ^ 1);
	v_add_u32_e32 v196, s37, v230
	v_add_u32_e32 v197, s37, v231
	v_add_u32_e32 v198, s37, v232
	v_add_u32_e32 v199, s56, v235
	v_add_u32_e32 v200, s56, v236
	s_waitcnt vmcnt(0)
	ds_write_b128 v196, v[204:207]
	ds_write_b128 v197, v[208:211]
	ds_write_b128 v198, v[212:215]
	ds_write_b128 v199, v[216:219]
	ds_write_b128 v200, v[220:223]
	v_pk_mul_f32 v[48:49], v[48:49], v[246:247] op_sel_hi:[1,0]
	v_pk_mul_f32 v[50:51], v[50:51], v[246:247] op_sel_hi:[1,0]
	v_pk_mul_f32 v[52:53], v[52:53], v[246:247] op_sel_hi:[1,0]
	v_pk_mul_f32 v[54:55], v[54:55], v[246:247] op_sel_hi:[1,0]
	v_pk_mul_f32 v[56:57], v[56:57], v[246:247] op_sel_hi:[1,0]
	v_pk_mul_f32 v[58:59], v[58:59], v[246:247] op_sel_hi:[1,0]
	v_pk_mul_f32 v[60:61], v[60:61], v[246:247] op_sel_hi:[1,0]
	v_pk_mul_f32 v[62:63], v[62:63], v[246:247] op_sel_hi:[1,0]
	s_waitcnt lgkmcnt(11)
	v_mfma_f32_32x32x16_bf16 v[48:63], v[168:171], v[184:187], v[48:63]
	v_pk_mul_f32 v[64:65], v[64:65], v[246:247] op_sel_hi:[1,0]
	v_pk_mul_f32 v[66:67], v[66:67], v[246:247] op_sel_hi:[1,0]
	v_pk_mul_f32 v[68:69], v[68:69], v[246:247] op_sel_hi:[1,0]
	v_pk_mul_f32 v[70:71], v[70:71], v[246:247] op_sel_hi:[1,0]
	ds_read_b64 v[168:169], v241 offset:9216
	ds_read_b64 v[170:171], v241 offset:9232
	s_waitcnt lgkmcnt(11)
	v_mfma_f32_32x32x16_bf16 v[48:63], v[172:175], v[188:191], v[48:63]
	v_pk_mul_f32 v[72:73], v[72:73], v[246:247] op_sel_hi:[1,0]
	v_pk_mul_f32 v[74:75], v[74:75], v[246:247] op_sel_hi:[1,0]
	v_pk_mul_f32 v[76:77], v[76:77], v[246:247] op_sel_hi:[1,0]
	v_pk_mul_f32 v[78:79], v[78:79], v[246:247] op_sel_hi:[1,0]
	ds_read_b64 v[172:173], v241 offset:9248
	ds_read_b64 v[174:175], v241 offset:9264
	s_waitcnt lgkmcnt(11)
	v_mfma_f32_32x32x16_bf16 v[64:79], v[176:179], v[184:187], v[64:79]
	v_pk_mul_f32 v[80:81], v[80:81], v[246:247] op_sel_hi:[1,0]
	v_pk_mul_f32 v[82:83], v[82:83], v[246:247] op_sel_hi:[1,0]
	v_pk_mul_f32 v[84:85], v[84:85], v[246:247] op_sel_hi:[1,0]
	v_pk_mul_f32 v[86:87], v[86:87], v[246:247] op_sel_hi:[1,0]
	ds_read_b64 v[176:177], v241 offset:13824
	ds_read_b64 v[178:179], v241 offset:13840
	s_waitcnt lgkmcnt(11)
	v_mfma_f32_32x32x16_bf16 v[64:79], v[180:183], v[188:191], v[64:79]
	v_pk_mul_f32 v[88:89], v[88:89], v[246:247] op_sel_hi:[1,0]
	v_pk_mul_f32 v[90:91], v[90:91], v[246:247] op_sel_hi:[1,0]
	v_pk_mul_f32 v[92:93], v[92:93], v[246:247] op_sel_hi:[1,0]
	v_pk_mul_f32 v[94:95], v[94:95], v[246:247] op_sel_hi:[1,0]
	ds_read_b64 v[180:181], v241 offset:13856
	ds_read_b64 v[182:183], v241 offset:13872
	s_waitcnt lgkmcnt(6)
	global_load_dwordx4 v[204:207], v224, s[4:5]
	global_load_dwordx4 v[208:211], v225, s[4:5]
	global_load_dwordx4 v[212:215], v226, s[4:5]
	global_load_dwordx4 v[216:219], v233, s[8:9]
	global_load_dwordx4 v[220:223], v234, s[8:9]
	v_mfma_f32_32x32x16_bf16 v[80:95], v[168:171], v[184:187], v[80:95]
	v_pk_mul_f32 v[96:97], v[96:97], v[246:247] op_sel_hi:[1,0]
	v_pk_mul_f32 v[98:99], v[98:99], v[246:247] op_sel_hi:[1,0]
	v_pk_mul_f32 v[100:101], v[100:101], v[246:247] op_sel_hi:[1,0]
	v_pk_mul_f32 v[102:103], v[102:103], v[246:247] op_sel_hi:[1,0]
	s_nop 1
	s_waitcnt lgkmcnt(4)
	v_mfma_f32_32x32x16_bf16 v[80:95], v[172:175], v[188:191], v[80:95]
	v_pk_mul_f32 v[104:105], v[104:105], v[246:247] op_sel_hi:[1,0]
	v_pk_mul_f32 v[106:107], v[106:107], v[246:247] op_sel_hi:[1,0]
	v_pk_mul_f32 v[108:109], v[108:109], v[246:247] op_sel_hi:[1,0]
	v_pk_mul_f32 v[110:111], v[110:111], v[246:247] op_sel_hi:[1,0]
	s_nop 1
	s_waitcnt lgkmcnt(2)
	v_mfma_f32_32x32x16_bf16 v[96:111], v[176:179], v[184:187], v[96:111]
	s_waitcnt lgkmcnt(0)
	v_mfma_f32_32x32x16_bf16 v[96:111], v[180:183], v[188:191], v[96:111]
	s_branch dn1_jn1
dn1_nr1:
	s_nop 1
	v_add_u32_e32 v196, s37, v230
	v_add_u32_e32 v197, s37, v231
	v_add_u32_e32 v198, s37, v232
	v_add_u32_e32 v199, s56, v235
	v_add_u32_e32 v200, s56, v236
	s_waitcnt vmcnt(0)
	ds_write_b128 v196, v[204:207]
	ds_write_b128 v197, v[208:211]
	ds_write_b128 v198, v[212:215]
	ds_write_b128 v199, v[216:219]
	ds_write_b128 v200, v[220:223]
	s_waitcnt lgkmcnt(11)
	v_mfma_f32_32x32x16_bf16 v[48:63], v[168:171], v[184:187], v[48:63]
	ds_read_b64 v[168:169], v241 offset:9216
	ds_read_b64 v[170:171], v241 offset:9232
	s_waitcnt lgkmcnt(11)
	v_mfma_f32_32x32x16_bf16 v[48:63], v[172:175], v[188:191], v[48:63]
	ds_read_b64 v[172:173], v241 offset:9248
	ds_read_b64 v[174:175], v241 offset:9264
	s_waitcnt lgkmcnt(11)
	v_mfma_f32_32x32x16_bf16 v[64:79], v[176:179], v[184:187], v[64:79]
	ds_read_b64 v[176:177], v241 offset:13824
	ds_read_b64 v[178:179], v241 offset:13840
	s_waitcnt lgkmcnt(11)
	v_mfma_f32_32x32x16_bf16 v[64:79], v[180:183], v[188:191], v[64:79]
	ds_read_b64 v[180:181], v241 offset:13856
	ds_read_b64 v[182:183], v241 offset:13872
	s_waitcnt lgkmcnt(6)
	global_load_dwordx4 v[204:207], v224, s[4:5]
	global_load_dwordx4 v[208:211], v225, s[4:5]
	global_load_dwordx4 v[212:215], v226, s[4:5]
	global_load_dwordx4 v[216:219], v233, s[8:9]
	global_load_dwordx4 v[220:223], v234, s[8:9]
	v_mfma_f32_32x32x16_bf16 v[80:95], v[168:171], v[184:187], v[80:95]
	s_waitcnt lgkmcnt(4)
	v_mfma_f32_32x32x16_bf16 v[80:95], v[172:175], v[188:191], v[80:95]
	s_waitcnt lgkmcnt(2)
	v_mfma_f32_32x32x16_bf16 v[96:111], v[176:179], v[184:187], v[96:111]
	s_waitcnt lgkmcnt(0)
	v_mfma_f32_32x32x16_bf16 v[96:111], v[180:183], v[188:191], v[96:111]
; template <int DK>
; DI void dense_attn_item(LAS unsigned char* lds, const bf16_t* Qb, int ldq, const bf16_t* Kb, int ldk, const bf16_t* Kpe, const bf16_t* Vt, int nkeys, float sl2, bf16_t* Ob) {
;     ...
;         for (int kc = 0; kc < 2; ++kc) {
;             f32x4 sacc[2][2];
; #pragma unroll
;             for (int kb = 0; kb < 2; ++kb) {
;                 sacc[0][kb] = (f32x4){0.f, 0.f, 0.f, 0.f}; sacc[1][kb] = (f32x4){0.f, 0.f, 0.f, 0.f};
; #pragma unroll
;                 for (int kh = 0; kh < KS / 2; ++kh) {
;                     const bf16x8 k0 = *(const LAS bf16x8*)(kb_ + ((2 * kc + kb) * 16 + r16) * KROW + (2 * kh) * 64 + q4 * 16);
;                     const bf16x8 k1 = *(const LAS bf16x8*)(kb_ + ((2 * kc + kb) * 16 + r16) * KROW + (2 * kh + 1) * 64 + q4 * 16);
;                     __builtin_amdgcn_s_setprio(1);
;                     sacc[0][kb] = MFMA16(k0, qf[0][2 * kh], sacc[0][kb]); sacc[1][kb] = MFMA16(k0, qf[1][2 * kh], sacc[1][kb]);
;                     sacc[0][kb] = MFMA16(k1, qf[0][2 * kh + 1], sacc[0][kb]); sacc[1][kb] = MFMA16(k1, qf[1][2 * kh + 1], sacc[1][kb]);
;                     __builtin_amdgcn_s_setprio(0);
;                 }
;             }
;             bf16x8 pb[2];
; #pragma unroll
;             for (int qg = 0; qg < 2; ++qg) {
;                 float mx = fmaxf(fmaxf(fmaxf(sacc[qg][0][0], sacc[qg][0][1]), fmaxf(sacc[qg][0][2], sacc[qg][0][3])), fmaxf(fmaxf(sacc[qg][1][0], sacc[qg][1][1]), fmaxf(sacc[qg][1][2], sacc[qg][1][3])));
;                 mx = fmaxf(mx, __shfl_xor(mx, 16)); mx = fmaxf(mx, __shfl_xor(mx, 32));
;                 const float mnew = fmaxf(mrun[qg], mx * sl2), alpha = fast_exp2(mrun[qg] - mnew);
;                 mrun[qg] = mnew;
;                 float ps = 0.f;
; #pragma unroll
;                 for (int kb = 0; kb < 2; ++kb)
; #pragma unroll
;                     for (int j = 0; j < 4; ++j) { const float pv = fast_exp2(sacc[qg][kb][j] * sl2 - mnew); sacc[qg][kb][j] = pv; ps += pv; }
;                 lsum[qg] = lsum[qg] * alpha + ps;
; #pragma unroll
;                 for (int d = 0; d < 8; ++d) oacc[qg][d] *= alpha;
;                 u32x4 w; w.x = cvt_pk_bf16(sacc[qg][0][0], sacc[qg][0][1]); w.y = cvt_pk_bf16(sacc[qg][0][2], sacc[qg][0][3]);
;                 w.z = cvt_pk_bf16(sacc[qg][1][0], sacc[qg][1][1]); w.w = cvt_pk_bf16(sacc[qg][1][2], sacc[qg][1][3]);
dn1_jn1:
	s_waitcnt lgkmcnt(0)
	s_barrier
	ds_read_b128 v[144:147], v240 offset:0
	ds_read_b128 v[148:151], v240 offset:32
	ds_read_b128 v[152:155], v240 offset:64
	ds_read_b128 v[156:159], v240 offset:96
	ds_read_b128 v[160:163], v240 offset:128
	ds_read_b128 v[164:167], v240 offset:160
	v_max3_f32 v193, v128, v129, v130
	v_max3_f32 v192, v131, v132, v133
	v_max3_f32 v193, v193, v134, v135
	v_max3_f32 v192, v192, v136, v137
	v_max3_f32 v193, v193, v138, v139
	v_max3_f32 v192, v192, v140, v141
	v_max3_f32 v193, v193, v142, v143
	v_max_f32_e32 v193, v193, v192
	v_mov_b32_e32 v192, v193
	s_nop 1
	s_waitcnt lgkmcnt(5)
	v_mfma_f32_32x32x16_bf16 v[112:127], v[144:147], v[0:3], 0
	v_permlane32_swap_b32_e32 v193, v192
	v_max_f32_e32 v193, v193, v192
	v_mul_f32_e32 v193, s22, v193
	v_max_f32_e32 v192, v242, v193
	v_sub_f32_e32 v193, v192, v242
	ds_read_b128 v[144:147], v240 offset:192
	s_waitcnt lgkmcnt(5)
	v_mfma_f32_32x32x16_bf16 v[112:127], v[148:151], v[4:7], v[112:127]
	v_cmp_gt_f32_e64 s[68:69], v193, s29
	s_cmp_lg_u64 s[68:69], 0
	s_cselect_b64 s[68:69], -1, 0
	v_cndmask_b32_e64 v192, v242, v192, s[68:69]
	v_sub_f32_e32 v193, v242, v192
	ds_read_b128 v[148:151], v240 offset:224
	s_waitcnt lgkmcnt(5)
	v_mfma_f32_32x32x16_bf16 v[112:127], v[152:155], v[8:11], v[112:127]
	v_exp_f32_e32 v246, v193
	v_mov_b32_e32 v242, v192
	v_pk_fma_f32 v[128:129], v[128:129], v[254:255], v[192:193] op_sel_hi:[1,0,0] neg_lo:[0,0,1] neg_hi:[0,0,1]
	v_pk_fma_f32 v[130:131], v[130:131], v[254:255], v[192:193] op_sel_hi:[1,0,0] neg_lo:[0,0,1] neg_hi:[0,0,1]
	v_pk_fma_f32 v[132:133], v[132:133], v[254:255], v[192:193] op_sel_hi:[1,0,0] neg_lo:[0,0,1] neg_hi:[0,0,1]
	ds_read_b128 v[152:155], v240 offset:256
	s_waitcnt lgkmcnt(5)
	v_mfma_f32_32x32x16_bf16 v[112:127], v[156:159], v[12:15], v[112:127]
	v_pk_fma_f32 v[134:135], v[134:135], v[254:255], v[192:193] op_sel_hi:[1,0,0] neg_lo:[0,0,1] neg_hi:[0,0,1]
	v_pk_fma_f32 v[136:137], v[136:137], v[254:255], v[192:193] op_sel_hi:[1,0,0] neg_lo:[0,0,1] neg_hi:[0,0,1]
	v_pk_fma_f32 v[138:139], v[138:139], v[254:255], v[192:193] op_sel_hi:[1,0,0] neg_lo:[0,0,1] neg_hi:[0,0,1]
	v_pk_fma_f32 v[140:141], v[140:141], v[254:255], v[192:193] op_sel_hi:[1,0,0] neg_lo:[0,0,1] neg_hi:[0,0,1]
	v_pk_fma_f32 v[142:143], v[142:143], v[254:255], v[192:193] op_sel_hi:[1,0,0] neg_lo:[0,0,1] neg_hi:[0,0,1]
	ds_read_b128 v[156:159], v240 offset:288
	s_waitcnt lgkmcnt(5)
	v_mfma_f32_32x32x16_bf16 v[112:127], v[160:163], v[16:19], v[112:127]
	v_exp_f32_e32 v128, v128
	v_exp_f32_e32 v129, v129
	v_exp_f32_e32 v130, v130
	v_exp_f32_e32 v131, v131
	v_exp_f32_e32 v132, v132
	ds_read_b128 v[160:163], v240 offset:320
	s_waitcnt lgkmcnt(5)
	v_mfma_f32_32x32x16_bf16 v[112:127], v[164:167], v[20:23], v[112:127]
	v_exp_f32_e32 v133, v133
	v_exp_f32_e32 v134, v134
	v_exp_f32_e32 v135, v135
	v_exp_f32_e32 v136, v136
	v_exp_f32_e32 v137, v137
	ds_read_b128 v[164:167], v240 offset:352
	s_waitcnt lgkmcnt(5)
	v_mfma_f32_32x32x16_bf16 v[112:127], v[144:147], v[24:27], v[112:127]
	v_exp_f32_e32 v138, v138
	v_exp_f32_e32 v139, v139
	v_exp_f32_e32 v140, v140
	v_exp_f32_e32 v141, v141
	v_exp_f32_e32 v142, v142
	ds_read_b64 v[168:169], v241 offset:64
	ds_read_b64 v[170:171], v241 offset:80
	s_waitcnt lgkmcnt(6)
	v_mfma_f32_32x32x16_bf16 v[112:127], v[148:151], v[28:31], v[112:127]
	v_exp_f32_e32 v143, v143
	v_pk_add_f32 v[196:197], v[128:129], v[130:131]
	v_pk_add_f32 v[198:199], v[132:133], v[134:135]
	v_pk_add_f32 v[196:197], v[196:197], v[136:137]
	v_pk_add_f32 v[198:199], v[198:199], v[138:139]
	ds_read_b64 v[172:173], v241 offset:96
	ds_read_b64 v[174:175], v241 offset:112
	s_waitcnt lgkmcnt(7)
	v_mfma_f32_32x32x16_bf16 v[112:127], v[152:155], v[32:35], v[112:127]
	v_pk_add_f32 v[196:197], v[196:197], v[140:141]
	v_pk_add_f32 v[198:199], v[198:199], v[142:143]
	v_pk_add_f32 v[196:197], v[196:197], v[198:199]
	v_add_f32_e32 v193, v196, v197
	v_fma_f32 v244, v244, v246, v193
	ds_read_b64 v[176:177], v241 offset:4672
	ds_read_b64 v[178:179], v241 offset:4688
	s_waitcnt lgkmcnt(8)
	v_mfma_f32_32x32x16_bf16 v[112:127], v[156:159], v[36:39], v[112:127]
	v_cvt_pk_bf16_f32 v184, v128, v129
	v_cvt_pk_bf16_f32 v185, v130, v131
	v_cvt_pk_bf16_f32 v186, v132, v133
	v_cvt_pk_bf16_f32 v187, v134, v135
	v_cvt_pk_bf16_f32 v188, v136, v137
	ds_read_b64 v[180:181], v241 offset:4704
	ds_read_b64 v[182:183], v241 offset:4720
	s_waitcnt lgkmcnt(9)
	v_mfma_f32_32x32x16_bf16 v[112:127], v[160:163], v[40:43], v[112:127]
	v_cvt_pk_bf16_f32 v189, v138, v139
	v_cvt_pk_bf16_f32 v190, v140, v141
	v_cvt_pk_bf16_f32 v191, v142, v143
	s_waitcnt lgkmcnt(8)
	v_mfma_f32_32x32x16_bf16 v[112:127], v[164:167], v[44:47], v[112:127]
	s_mov_b64 vcc, s[68:69]
	s_cbranch_vccz dn1_nr2
; #define LAS __attribute__((address_space(3)))
; #define MFMA16(a, b, c) __builtin_amdgcn_mfma_f32_16x16x32_bf16((a), (b), (c), 0, 0, 0)
; template <int DK>
; DI void dense_attn_item(LAS unsigned char* lds, const bf16_t* Qb, int ldq, const bf16_t* Kb, int ldk, const bf16_t* Kpe, const bf16_t* Vt, int nkeys, float sl2, bf16_t* Ob) {
;     ...
; #pragma unroll
;             for (int dh = 0; dh < 4; ++dh) {
;                 bf16x8 vfr[2];
; #pragma unroll
;                 for (int d4 = 0; d4 < 2; ++d4) {
;                     const int d = dh * 2 + d4;
;                     const u32x2 lo = *(const LAS u32x2*)(vb_ + (d * 16 + r16) * VROW + (kc * 32 + q4 * 4) * 2);
;                     const u32x2 hi = *(const LAS u32x2*)(vb_ + (d * 16 + r16) * VROW + (kc * 32 + 16 + q4 * 4) * 2);
;                     u32x4 w; w.x = lo.x; w.y = lo.y; w.z = hi.x; w.w = hi.y;
;                     vfr[d4] = __builtin_bit_cast(bf16x8, w);
;                 }
;                 __builtin_amdgcn_s_setprio(1);
; #pragma unroll
;                 for (int d4 = 0; d4 < 2; ++d4) { const int d = dh * 2 + d4; oacc[0][d] = MFMA16(vfr[d4], pb[0], oacc[0][d]); oacc[1][d] = MFMA16(vfr[d4], pb[1], oacc[1][d]); }
;                 __builtin_amdgcn_s_setprio(0);
;             }
;         }
;         if (kt + 1 < ntiles) DA_STORE(cur ^ 1);
	v_pk_mul_f32 v[48:49], v[48:49], v[246:247] op_sel_hi:[1,0]
	v_pk_mul_f32 v[50:51], v[50:51], v[246:247] op_sel_hi:[1,0]
	v_pk_mul_f32 v[52:53], v[52:53], v[246:247] op_sel_hi:[1,0]
	v_pk_mul_f32 v[54:55], v[54:55], v[246:247] op_sel_hi:[1,0]
	v_pk_mul_f32 v[56:57], v[56:57], v[246:247] op_sel_hi:[1,0]
	v_pk_mul_f32 v[58:59], v[58:59], v[246:247] op_sel_hi:[1,0]
	v_pk_mul_f32 v[60:61], v[60:61], v[246:247] op_sel_hi:[1,0]
	v_pk_mul_f32 v[62:63], v[62:63], v[246:247] op_sel_hi:[1,0]
	s_waitcnt lgkmcnt(6)
	v_mfma_f32_32x32x16_bf16 v[48:63], v[168:171], v[184:187], v[48:63]
	v_pk_mul_f32 v[64:65], v[64:65], v[246:247] op_sel_hi:[1,0]
	v_pk_mul_f32 v[66:67], v[66:67], v[246:247] op_sel_hi:[1,0]
	v_pk_mul_f32 v[68:69], v[68:69], v[246:247] op_sel_hi:[1,0]
	v_pk_mul_f32 v[70:71], v[70:71], v[246:247] op_sel_hi:[1,0]
	ds_read_b64 v[168:169], v241 offset:9280
	ds_read_b64 v[170:171], v241 offset:9296
	s_waitcnt lgkmcnt(6)
	v_mfma_f32_32x32x16_bf16 v[48:63], v[172:175], v[188:191], v[48:63]
	v_pk_mul_f32 v[72:73], v[72:73], v[246:247] op_sel_hi:[1,0]
	v_pk_mul_f32 v[74:75], v[74:75], v[246:247] op_sel_hi:[1,0]
	v_pk_mul_f32 v[76:77], v[76:77], v[246:247] op_sel_hi:[1,0]
	v_pk_mul_f32 v[78:79], v[78:79], v[246:247] op_sel_hi:[1,0]
	ds_read_b64 v[172:173], v241 offset:9312
	ds_read_b64 v[174:175], v241 offset:9328
	s_waitcnt lgkmcnt(6)
	v_mfma_f32_32x32x16_bf16 v[64:79], v[176:179], v[184:187], v[64:79]
	v_pk_mul_f32 v[80:81], v[80:81], v[246:247] op_sel_hi:[1,0]
	v_pk_mul_f32 v[82:83], v[82:83], v[246:247] op_sel_hi:[1,0]
	v_pk_mul_f32 v[84:85], v[84:85], v[246:247] op_sel_hi:[1,0]
	v_pk_mul_f32 v[86:87], v[86:87], v[246:247] op_sel_hi:[1,0]
	ds_read_b64 v[176:177], v241 offset:13888
	ds_read_b64 v[178:179], v241 offset:13904
	ds_read_b128 v[144:147], v240 offset:12800
	s_waitcnt lgkmcnt(7)
	v_mfma_f32_32x32x16_bf16 v[64:79], v[180:183], v[188:191], v[64:79]
	v_pk_mul_f32 v[88:89], v[88:89], v[246:247] op_sel_hi:[1,0]
	v_pk_mul_f32 v[90:91], v[90:91], v[246:247] op_sel_hi:[1,0]
	v_pk_mul_f32 v[92:93], v[92:93], v[246:247] op_sel_hi:[1,0]
	v_pk_mul_f32 v[94:95], v[94:95], v[246:247] op_sel_hi:[1,0]
	ds_read_b64 v[180:181], v241 offset:13920
	ds_read_b64 v[182:183], v241 offset:13936
	ds_read_b128 v[148:151], v240 offset:12832
	s_waitcnt lgkmcnt(8)
	v_mfma_f32_32x32x16_bf16 v[80:95], v[168:171], v[184:187], v[80:95]
	v_pk_mul_f32 v[96:97], v[96:97], v[246:247] op_sel_hi:[1,0]
	v_pk_mul_f32 v[98:99], v[98:99], v[246:247] op_sel_hi:[1,0]
	v_pk_mul_f32 v[100:101], v[100:101], v[246:247] op_sel_hi:[1,0]
	v_pk_mul_f32 v[102:103], v[102:103], v[246:247] op_sel_hi:[1,0]
	s_nop 1
	ds_read_b128 v[152:155], v240 offset:12864
	s_waitcnt lgkmcnt(7)
	v_mfma_f32_32x32x16_bf16 v[80:95], v[172:175], v[188:191], v[80:95]
	v_pk_mul_f32 v[104:105], v[104:105], v[246:247] op_sel_hi:[1,0]
	v_pk_mul_f32 v[106:107], v[106:107], v[246:247] op_sel_hi:[1,0]
	v_pk_mul_f32 v[108:109], v[108:109], v[246:247] op_sel_hi:[1,0]
	v_pk_mul_f32 v[110:111], v[110:111], v[246:247] op_sel_hi:[1,0]
	s_nop 1
	ds_read_b128 v[156:159], v240 offset:12896
	s_waitcnt lgkmcnt(6)
	v_mfma_f32_32x32x16_bf16 v[96:111], v[176:179], v[184:187], v[96:111]
	ds_read_b128 v[160:163], v240 offset:12928
	s_waitcnt lgkmcnt(4)
	v_mfma_f32_32x32x16_bf16 v[96:111], v[180:183], v[188:191], v[96:111]
	ds_read_b128 v[164:167], v240 offset:12960
	s_branch dn1_jn2
dn1_nr2:
	s_nop 1
	s_waitcnt lgkmcnt(6)
	v_mfma_f32_32x32x16_bf16 v[48:63], v[168:171], v[184:187], v[48:63]
	ds_read_b64 v[168:169], v241 offset:9280
	ds_read_b64 v[170:171], v241 offset:9296
	s_waitcnt lgkmcnt(6)
	v_mfma_f32_32x32x16_bf16 v[48:63], v[172:175], v[188:191], v[48:63]
	ds_read_b64 v[172:173], v241 offset:9312
	ds_read_b64 v[174:175], v241 offset:9328
	s_waitcnt lgkmcnt(6)
	v_mfma_f32_32x32x16_bf16 v[64:79], v[176:179], v[184:187], v[64:79]
	ds_read_b64 v[176:177], v241 offset:13888
	ds_read_b64 v[178:179], v241 offset:13904
	ds_read_b128 v[144:147], v240 offset:12800
	s_waitcnt lgkmcnt(7)
	v_mfma_f32_32x32x16_bf16 v[64:79], v[180:183], v[188:191], v[64:79]
	ds_read_b64 v[180:181], v241 offset:13920
	ds_read_b64 v[182:183], v241 offset:13936
	ds_read_b128 v[148:151], v240 offset:12832
	s_waitcnt lgkmcnt(8)
	v_mfma_f32_32x32x16_bf16 v[80:95], v[168:171], v[184:187], v[80:95]
	ds_read_b128 v[152:155], v240 offset:12864
	s_waitcnt lgkmcnt(7)
	v_mfma_f32_32x32x16_bf16 v[80:95], v[172:175], v[188:191], v[80:95]
	ds_read_b128 v[156:159], v240 offset:12896
	s_waitcnt lgkmcnt(6)
	v_mfma_f32_32x32x16_bf16 v[96:111], v[176:179], v[184:187], v[96:111]
	ds_read_b128 v[160:163], v240 offset:12928
	s_waitcnt lgkmcnt(4)
	v_mfma_f32_32x32x16_bf16 v[96:111], v[180:183], v[188:191], v[96:111]
	ds_read_b128 v[164:167], v240 offset:12960
